# glds issued first in each load segment, interleaved with ds_reads, s_nops removed (5 big GEMM loops)
# speedup vs baseline: 1.0114x; 1.0025x over previous
.LBB0_272:
	s_mov_b32 m0, s40
	ds_read_b128 v[154:157], v148
	global_load_lds_dwordx4 v142, s[22:23]
	s_mov_b32 m0, s41
	ds_read_b128 v[158:161], v148 offset:1024
	global_load_lds_dwordx4 v144, s[22:23]
	ds_read_b128 v[164:167], v148 offset:2048
	ds_read_b128 v[168:171], v148 offset:3072
	ds_read_b128 v[172:175], v149
	ds_read_b128 v[176:179], v149 offset:1024
	ds_read_b128 v[180:183], v149 offset:2048
	ds_read_b128 v[184:187], v149 offset:3072
	s_add_u32 s24, s22, 0xfff00080
	s_addc_u32 s25, s23, -1
	s_cmp_eq_u32 s56, 60
	s_cselect_b32 s27, s51, s25
	s_cselect_b32 s26, s52, s24
	s_cselect_b32 s25, s7, s55
	s_cselect_b32 s24, s53, s54
	ds_read_b128 v[188:191], v150
	ds_read_b128 v[192:195], v150 offset:1024
	ds_read_b128 v[196:199], v150 offset:2048
	ds_read_b128 v[200:203], v150 offset:3072
	ds_read_b128 v[204:207], v150 offset:4096
	ds_read_b128 v[208:211], v150 offset:5120
	ds_read_b128 v[212:215], v150 offset:6144
	ds_read_b128 v[216:219], v150 offset:7168
	s_waitcnt vmcnt(8)
	s_waitcnt lgkmcnt(0)
	s_barrier
	s_setprio 1
	s_waitcnt lgkmcnt(0)
	v_mfma_f32_16x16x32_bf16 v[126:129], v[154:157], v[188:191], v[126:129]
	v_mfma_f32_16x16x32_bf16 v[122:125], v[164:167], v[188:191], v[122:125]
	v_mfma_f32_16x16x32_bf16 v[118:121], v[154:157], v[196:199], v[118:121]
	v_mfma_f32_16x16x32_bf16 v[114:117], v[164:167], v[196:199], v[114:117]
	v_mfma_f32_16x16x32_bf16 v[102:105], v[154:157], v[204:207], v[102:105]
	v_mfma_f32_16x16x32_bf16 v[98:101], v[164:167], v[204:207], v[98:101]
	v_mfma_f32_16x16x32_bf16 v[86:89], v[154:157], v[212:215], v[86:89]
	v_mfma_f32_16x16x32_bf16 v[82:85], v[164:167], v[212:215], v[82:85]
	v_mfma_f32_16x16x32_bf16 v[126:129], v[158:161], v[192:195], v[126:129]
	v_mfma_f32_16x16x32_bf16 v[122:125], v[168:171], v[192:195], v[122:125]
	v_mfma_f32_16x16x32_bf16 v[118:121], v[158:161], v[200:203], v[118:121]
	v_mfma_f32_16x16x32_bf16 v[114:117], v[168:171], v[200:203], v[114:117]
	v_mfma_f32_16x16x32_bf16 v[102:105], v[158:161], v[208:211], v[102:105]
	v_mfma_f32_16x16x32_bf16 v[98:101], v[168:171], v[208:211], v[98:101]
	v_mfma_f32_16x16x32_bf16 v[86:89], v[158:161], v[216:219], v[86:89]
	v_mfma_f32_16x16x32_bf16 v[82:85], v[168:171], v[216:219], v[82:85]
	s_setprio 0
	s_setprio 1
	v_mfma_f32_16x16x32_bf16 v[110:113], v[172:175], v[188:191], v[110:113]
	v_mfma_f32_16x16x32_bf16 v[106:109], v[180:183], v[188:191], v[106:109]
	v_mfma_f32_16x16x32_bf16 v[94:97], v[172:175], v[196:199], v[94:97]
	v_mfma_f32_16x16x32_bf16 v[90:93], v[180:183], v[196:199], v[90:93]
	v_mfma_f32_16x16x32_bf16 v[78:81], v[172:175], v[204:207], v[78:81]
	v_mfma_f32_16x16x32_bf16 v[74:77], v[180:183], v[204:207], v[74:77]
	v_mfma_f32_16x16x32_bf16 v[70:73], v[172:175], v[212:215], v[70:73]
	v_mfma_f32_16x16x32_bf16 v[66:69], v[180:183], v[212:215], v[66:69]
	v_mfma_f32_16x16x32_bf16 v[110:113], v[176:179], v[192:195], v[110:113]
	v_mfma_f32_16x16x32_bf16 v[106:109], v[184:187], v[192:195], v[106:109]
	v_mfma_f32_16x16x32_bf16 v[94:97], v[176:179], v[200:203], v[94:97]
	v_mfma_f32_16x16x32_bf16 v[90:93], v[184:187], v[200:203], v[90:93]
	v_mfma_f32_16x16x32_bf16 v[78:81], v[176:179], v[208:211], v[78:81]
	v_mfma_f32_16x16x32_bf16 v[74:77], v[184:187], v[208:211], v[74:77]
	v_mfma_f32_16x16x32_bf16 v[70:73], v[176:179], v[216:219], v[70:73]
	v_mfma_f32_16x16x32_bf16 v[66:69], v[184:187], v[216:219], v[66:69]
	s_setprio 0
	s_barrier
	s_mov_b32 m0, s42
	s_add_u32 s58, s24, 0x100000
	global_load_lds_dwordx4 v132, s[24:25]
	s_mov_b32 m0, s43
	s_addc_u32 s59, s25, 0
	global_load_lds_dwordx4 v136, s[24:25]
	s_mov_b32 m0, s44
	ds_read_b128 v[188:191], v150 offset:16384
	global_load_lds_dwordx4 v132, s[58:59]
	s_mov_b32 m0, s45
	ds_read_b128 v[192:195], v150 offset:17408
	global_load_lds_dwordx4 v136, s[58:59]
	s_mov_b32 m0, s30
	ds_read_b128 v[196:199], v150 offset:18432
	global_load_lds_dwordx4 v130, s[26:27]
	s_mov_b32 m0, s31
	ds_read_b128 v[200:203], v150 offset:19456
	global_load_lds_dwordx4 v134, s[26:27]
	ds_read_b128 v[204:207], v150 offset:20480
	ds_read_b128 v[208:211], v150 offset:21504
	ds_read_b128 v[212:215], v150 offset:22528
	ds_read_b128 v[216:219], v150 offset:23552
	s_waitcnt vmcnt(8)
	s_waitcnt lgkmcnt(0)
	s_barrier
	s_setprio 1
	s_waitcnt lgkmcnt(0)
	v_mfma_f32_16x16x32_bf16 v[62:65], v[154:157], v[188:191], v[62:65]
	v_mfma_f32_16x16x32_bf16 v[58:61], v[164:167], v[188:191], v[58:61]
	v_mfma_f32_16x16x32_bf16 v[54:57], v[154:157], v[196:199], v[54:57]
	v_mfma_f32_16x16x32_bf16 v[50:53], v[164:167], v[196:199], v[50:53]
	v_mfma_f32_16x16x32_bf16 v[38:41], v[154:157], v[204:207], v[38:41]
	v_mfma_f32_16x16x32_bf16 v[34:37], v[164:167], v[204:207], v[34:37]
	v_mfma_f32_16x16x32_bf16 v[22:25], v[154:157], v[212:215], v[22:25]
	v_mfma_f32_16x16x32_bf16 v[18:21], v[164:167], v[212:215], v[18:21]
	v_mfma_f32_16x16x32_bf16 v[62:65], v[158:161], v[192:195], v[62:65]
	v_mfma_f32_16x16x32_bf16 v[58:61], v[168:171], v[192:195], v[58:61]
	v_mfma_f32_16x16x32_bf16 v[54:57], v[158:161], v[200:203], v[54:57]
	v_mfma_f32_16x16x32_bf16 v[50:53], v[168:171], v[200:203], v[50:53]
	v_mfma_f32_16x16x32_bf16 v[38:41], v[158:161], v[208:211], v[38:41]
	v_mfma_f32_16x16x32_bf16 v[34:37], v[168:171], v[208:211], v[34:37]
	v_mfma_f32_16x16x32_bf16 v[22:25], v[158:161], v[216:219], v[22:25]
	v_mfma_f32_16x16x32_bf16 v[18:21], v[168:171], v[216:219], v[18:21]
	s_setprio 0
	s_setprio 1
	v_mfma_f32_16x16x32_bf16 v[46:49], v[172:175], v[188:191], v[46:49]
	v_mfma_f32_16x16x32_bf16 v[42:45], v[180:183], v[188:191], v[42:45]
	v_mfma_f32_16x16x32_bf16 v[30:33], v[172:175], v[196:199], v[30:33]
	v_mfma_f32_16x16x32_bf16 v[26:29], v[180:183], v[196:199], v[26:29]
	v_mfma_f32_16x16x32_bf16 v[14:17], v[172:175], v[204:207], v[14:17]
	v_mfma_f32_16x16x32_bf16 v[10:13], v[180:183], v[204:207], v[10:13]
	v_mfma_f32_16x16x32_bf16 v[6:9], v[172:175], v[212:215], v[6:9]
	v_mfma_f32_16x16x32_bf16 v[2:5], v[180:183], v[212:215], v[2:5]
	v_mfma_f32_16x16x32_bf16 v[46:49], v[176:179], v[192:195], v[46:49]
	v_mfma_f32_16x16x32_bf16 v[42:45], v[184:187], v[192:195], v[42:45]
	v_mfma_f32_16x16x32_bf16 v[30:33], v[176:179], v[200:203], v[30:33]
	v_mfma_f32_16x16x32_bf16 v[26:29], v[184:187], v[200:203], v[26:29]
	v_mfma_f32_16x16x32_bf16 v[14:17], v[176:179], v[208:211], v[14:17]
	v_mfma_f32_16x16x32_bf16 v[10:13], v[184:187], v[208:211], v[10:13]
	v_mfma_f32_16x16x32_bf16 v[6:9], v[176:179], v[216:219], v[6:9]
	v_mfma_f32_16x16x32_bf16 v[2:5], v[184:187], v[216:219], v[2:5]
	s_setprio 0
	s_barrier
	s_add_u32 s26, s26, 0x100000
	s_addc_u32 s27, s27, 0
	s_mov_b32 m0, s33
	ds_read_b128 v[154:157], v151
	global_load_lds_dwordx4 v130, s[26:27]
	s_mov_b32 m0, s34
	ds_read_b128 v[158:161], v151 offset:1024
	global_load_lds_dwordx4 v134, s[26:27]
	ds_read_b128 v[164:167], v151 offset:2048
	ds_read_b128 v[168:171], v151 offset:3072
	ds_read_b128 v[172:175], v152
	ds_read_b128 v[176:179], v152 offset:1024
	ds_read_b128 v[180:183], v152 offset:2048
	ds_read_b128 v[184:187], v152 offset:3072
	ds_read_b128 v[188:191], v150 offset:32768
	ds_read_b128 v[192:195], v150 offset:33792
	ds_read_b128 v[196:199], v150 offset:34816
	ds_read_b128 v[200:203], v150 offset:35840
	ds_read_b128 v[204:207], v150 offset:36864
	ds_read_b128 v[208:211], v150 offset:37888
	ds_read_b128 v[212:215], v150 offset:38912
	ds_read_b128 v[216:219], v150 offset:39936
	s_waitcnt vmcnt(8)
	s_waitcnt lgkmcnt(0)
	s_barrier
	s_setprio 1
	s_waitcnt lgkmcnt(0)
	v_mfma_f32_16x16x32_bf16 v[126:129], v[154:157], v[188:191], v[126:129]
	v_mfma_f32_16x16x32_bf16 v[122:125], v[164:167], v[188:191], v[122:125]
	v_mfma_f32_16x16x32_bf16 v[118:121], v[154:157], v[196:199], v[118:121]
	v_mfma_f32_16x16x32_bf16 v[114:117], v[164:167], v[196:199], v[114:117]
	v_mfma_f32_16x16x32_bf16 v[102:105], v[154:157], v[204:207], v[102:105]
	v_mfma_f32_16x16x32_bf16 v[98:101], v[164:167], v[204:207], v[98:101]
	v_mfma_f32_16x16x32_bf16 v[86:89], v[154:157], v[212:215], v[86:89]
	v_mfma_f32_16x16x32_bf16 v[82:85], v[164:167], v[212:215], v[82:85]
	v_mfma_f32_16x16x32_bf16 v[126:129], v[158:161], v[192:195], v[126:129]
	v_mfma_f32_16x16x32_bf16 v[122:125], v[168:171], v[192:195], v[122:125]
	v_mfma_f32_16x16x32_bf16 v[118:121], v[158:161], v[200:203], v[118:121]
	v_mfma_f32_16x16x32_bf16 v[114:117], v[168:171], v[200:203], v[114:117]
	v_mfma_f32_16x16x32_bf16 v[102:105], v[158:161], v[208:211], v[102:105]
	v_mfma_f32_16x16x32_bf16 v[98:101], v[168:171], v[208:211], v[98:101]
	v_mfma_f32_16x16x32_bf16 v[86:89], v[158:161], v[216:219], v[86:89]
	v_mfma_f32_16x16x32_bf16 v[82:85], v[168:171], v[216:219], v[82:85]
	s_setprio 0
	s_setprio 1
	v_mfma_f32_16x16x32_bf16 v[110:113], v[172:175], v[188:191], v[110:113]
	v_mfma_f32_16x16x32_bf16 v[106:109], v[180:183], v[188:191], v[106:109]
	v_mfma_f32_16x16x32_bf16 v[94:97], v[172:175], v[196:199], v[94:97]
	v_mfma_f32_16x16x32_bf16 v[90:93], v[180:183], v[196:199], v[90:93]
	v_mfma_f32_16x16x32_bf16 v[78:81], v[172:175], v[204:207], v[78:81]
	v_mfma_f32_16x16x32_bf16 v[74:77], v[180:183], v[204:207], v[74:77]
	v_mfma_f32_16x16x32_bf16 v[70:73], v[172:175], v[212:215], v[70:73]
	v_mfma_f32_16x16x32_bf16 v[66:69], v[180:183], v[212:215], v[66:69]
	v_mfma_f32_16x16x32_bf16 v[110:113], v[176:179], v[192:195], v[110:113]
	v_mfma_f32_16x16x32_bf16 v[106:109], v[184:187], v[192:195], v[106:109]
	v_mfma_f32_16x16x32_bf16 v[94:97], v[176:179], v[200:203], v[94:97]
	v_mfma_f32_16x16x32_bf16 v[90:93], v[184:187], v[200:203], v[90:93]
	v_mfma_f32_16x16x32_bf16 v[78:81], v[176:179], v[208:211], v[78:81]
	v_mfma_f32_16x16x32_bf16 v[74:77], v[184:187], v[208:211], v[74:77]
	v_mfma_f32_16x16x32_bf16 v[70:73], v[176:179], v[216:219], v[70:73]
	v_mfma_f32_16x16x32_bf16 v[66:69], v[184:187], v[216:219], v[66:69]
	s_setprio 0
	s_barrier
	s_mov_b32 m0, s47
	s_add_u32 s24, s24, 0x80
	s_addc_u32 s25, s25, 0
	global_load_lds_dwordx4 v132, s[24:25]
	s_mov_b32 m0, s48
	s_add_u32 s58, s26, 0xfff00080
	s_addc_u32 s59, s27, -1
	global_load_lds_dwordx4 v136, s[24:25]
	s_add_i32 s26, s46, s29
	s_mov_b32 m0, s26
	s_add_u32 s24, s24, 0x100000
	s_addc_u32 s25, s25, 0
	global_load_lds_dwordx4 v132, s[24:25]
	s_add_i32 m0, s26, 0x2000
	ds_read_b128 v[188:191], v150 offset:49152
	global_load_lds_dwordx4 v136, s[24:25]
	s_mov_b32 m0, s36
	ds_read_b128 v[192:195], v150 offset:50176
	global_load_lds_dwordx4 v130, s[58:59]
	s_mov_b32 m0, s37
	ds_read_b128 v[196:199], v150 offset:51200
	global_load_lds_dwordx4 v134, s[58:59]
	ds_read_b128 v[200:203], v150 offset:52224
	ds_read_b128 v[204:207], v150 offset:53248
	ds_read_b128 v[208:211], v150 offset:54272
	ds_read_b128 v[212:215], v150 offset:55296
	ds_read_b128 v[216:219], v150 offset:56320
	s_waitcnt vmcnt(8)
	s_waitcnt lgkmcnt(0)
	s_barrier
	s_setprio 1
	s_waitcnt lgkmcnt(0)
	v_mfma_f32_16x16x32_bf16 v[62:65], v[154:157], v[188:191], v[62:65]
	v_mfma_f32_16x16x32_bf16 v[58:61], v[164:167], v[188:191], v[58:61]
	v_mfma_f32_16x16x32_bf16 v[54:57], v[154:157], v[196:199], v[54:57]
	v_mfma_f32_16x16x32_bf16 v[50:53], v[164:167], v[196:199], v[50:53]
	v_mfma_f32_16x16x32_bf16 v[38:41], v[154:157], v[204:207], v[38:41]
	v_mfma_f32_16x16x32_bf16 v[34:37], v[164:167], v[204:207], v[34:37]
	v_mfma_f32_16x16x32_bf16 v[22:25], v[154:157], v[212:215], v[22:25]
	v_mfma_f32_16x16x32_bf16 v[18:21], v[164:167], v[212:215], v[18:21]
	v_mfma_f32_16x16x32_bf16 v[62:65], v[158:161], v[192:195], v[62:65]
	v_mfma_f32_16x16x32_bf16 v[58:61], v[168:171], v[192:195], v[58:61]
	v_mfma_f32_16x16x32_bf16 v[54:57], v[158:161], v[200:203], v[54:57]
	v_mfma_f32_16x16x32_bf16 v[50:53], v[168:171], v[200:203], v[50:53]
	v_mfma_f32_16x16x32_bf16 v[38:41], v[158:161], v[208:211], v[38:41]
	v_mfma_f32_16x16x32_bf16 v[34:37], v[168:171], v[208:211], v[34:37]
	v_mfma_f32_16x16x32_bf16 v[22:25], v[158:161], v[216:219], v[22:25]
	v_mfma_f32_16x16x32_bf16 v[18:21], v[168:171], v[216:219], v[18:21]
	s_setprio 0
	s_setprio 1
	v_mfma_f32_16x16x32_bf16 v[46:49], v[172:175], v[188:191], v[46:49]
	v_mfma_f32_16x16x32_bf16 v[42:45], v[180:183], v[188:191], v[42:45]
	v_mfma_f32_16x16x32_bf16 v[30:33], v[172:175], v[196:199], v[30:33]
	v_mfma_f32_16x16x32_bf16 v[26:29], v[180:183], v[196:199], v[26:29]
	v_mfma_f32_16x16x32_bf16 v[14:17], v[172:175], v[204:207], v[14:17]
	v_mfma_f32_16x16x32_bf16 v[10:13], v[180:183], v[204:207], v[10:13]
	v_mfma_f32_16x16x32_bf16 v[6:9], v[172:175], v[212:215], v[6:9]
	v_mfma_f32_16x16x32_bf16 v[2:5], v[180:183], v[212:215], v[2:5]
	v_mfma_f32_16x16x32_bf16 v[46:49], v[176:179], v[192:195], v[46:49]
	v_mfma_f32_16x16x32_bf16 v[42:45], v[184:187], v[192:195], v[42:45]
	v_mfma_f32_16x16x32_bf16 v[30:33], v[176:179], v[200:203], v[30:33]
	v_mfma_f32_16x16x32_bf16 v[26:29], v[184:187], v[200:203], v[26:29]
	v_mfma_f32_16x16x32_bf16 v[14:17], v[176:179], v[208:211], v[14:17]
	v_mfma_f32_16x16x32_bf16 v[10:13], v[184:187], v[208:211], v[10:13]
	v_mfma_f32_16x16x32_bf16 v[6:9], v[176:179], v[216:219], v[6:9]
	v_mfma_f32_16x16x32_bf16 v[2:5], v[184:187], v[216:219], v[2:5]
	s_setprio 0
	s_barrier
	s_add_i32 s56, s56, 2
	s_add_u32 s22, s22, 0x100
	s_addc_u32 s23, s23, 0
	s_add_u32 s54, s54, 0x100
	s_addc_u32 s55, s55, 0
	s_cmp_gt_u32 s56, 61
	s_cbranch_scc0 .LBB0_272
	s_and_b64 vcc, exec, s[16:17]
	s_cbranch_vccz .LBB0_277
	s_barrier
	v_lshl_add_u32 v138, s50, 8, v1
	s_cmp_gt_i32 s49, 63
	s_mov_b64 s[22:23], -1
	s_cbranch_scc1 .LBB0_278

.LBB0_1172:
	s_mov_b32 m0, s42
	ds_read_b128 v[142:145], v148
	global_load_lds_dwordx4 v138, s[20:21]
	s_mov_b32 m0, s43
	ds_read_b128 v[154:157], v148 offset:1024
	global_load_lds_dwordx4 v140, s[20:21]
	ds_read_b128 v[158:161], v148 offset:2048
	ds_read_b128 v[168:171], v148 offset:3072
	ds_read_b128 v[176:179], v149
	ds_read_b128 v[180:183], v149 offset:1024
	ds_read_b128 v[184:187], v149 offset:2048
	ds_read_b128 v[188:191], v149 offset:3072
	s_add_u32 s22, s20, 0xfff00080
	s_addc_u32 s23, s21, -1
	s_cmp_eq_u32 s61, 60
	s_cselect_b32 s25, s54, s23
	s_cselect_b32 s24, s55, s22
	s_cselect_b32 s23, s7, s60
	s_cselect_b32 s22, s56, s57
	ds_read_b128 v[192:195], v150
	ds_read_b128 v[202:205], v150 offset:1024
	ds_read_b128 v[206:209], v150 offset:2048
	ds_read_b128 v[210:213], v150 offset:3072
	ds_read_b128 v[214:217], v150 offset:4096
	ds_read_b128 v[218:221], v150 offset:5120
	ds_read_b128 v[222:225], v150 offset:6144
	ds_read_b128 v[226:229], v150 offset:7168
	s_waitcnt vmcnt(8)
	s_waitcnt lgkmcnt(0)
	s_barrier
	s_setprio 1
	s_waitcnt lgkmcnt(0)
	v_mfma_f32_16x16x32_bf16 v[126:129], v[142:145], v[192:195], v[126:129]
	v_mfma_f32_16x16x32_bf16 v[118:121], v[158:161], v[192:195], v[118:121]
	v_mfma_f32_16x16x32_bf16 v[110:113], v[142:145], v[206:209], v[110:113]
	v_mfma_f32_16x16x32_bf16 v[102:105], v[158:161], v[206:209], v[102:105]
	v_mfma_f32_16x16x32_bf16 v[94:97], v[142:145], v[214:217], v[94:97]
	v_mfma_f32_16x16x32_bf16 v[86:89], v[158:161], v[214:217], v[86:89]
	v_mfma_f32_16x16x32_bf16 v[78:81], v[142:145], v[222:225], v[78:81]
	v_mfma_f32_16x16x32_bf16 v[70:73], v[158:161], v[222:225], v[70:73]
	v_mfma_f32_16x16x32_bf16 v[126:129], v[154:157], v[202:205], v[126:129]
	v_mfma_f32_16x16x32_bf16 v[118:121], v[168:171], v[202:205], v[118:121]
	v_mfma_f32_16x16x32_bf16 v[110:113], v[154:157], v[210:213], v[110:113]
	v_mfma_f32_16x16x32_bf16 v[102:105], v[168:171], v[210:213], v[102:105]
	v_mfma_f32_16x16x32_bf16 v[94:97], v[154:157], v[218:221], v[94:97]
	v_mfma_f32_16x16x32_bf16 v[86:89], v[168:171], v[218:221], v[86:89]
	v_mfma_f32_16x16x32_bf16 v[78:81], v[154:157], v[226:229], v[78:81]
	v_mfma_f32_16x16x32_bf16 v[70:73], v[168:171], v[226:229], v[70:73]
	s_setprio 0
	s_setprio 1
	v_mfma_f32_16x16x32_bf16 v[122:125], v[176:179], v[192:195], v[122:125]
	v_mfma_f32_16x16x32_bf16 v[114:117], v[184:187], v[192:195], v[114:117]
	v_mfma_f32_16x16x32_bf16 v[106:109], v[176:179], v[206:209], v[106:109]
	v_mfma_f32_16x16x32_bf16 v[98:101], v[184:187], v[206:209], v[98:101]
	v_mfma_f32_16x16x32_bf16 v[90:93], v[176:179], v[214:217], v[90:93]
	v_mfma_f32_16x16x32_bf16 v[82:85], v[184:187], v[214:217], v[82:85]
	v_mfma_f32_16x16x32_bf16 v[74:77], v[176:179], v[222:225], v[74:77]
	v_mfma_f32_16x16x32_bf16 v[66:69], v[184:187], v[222:225], v[66:69]
	v_mfma_f32_16x16x32_bf16 v[122:125], v[180:183], v[202:205], v[122:125]
	v_mfma_f32_16x16x32_bf16 v[114:117], v[188:191], v[202:205], v[114:117]
	v_mfma_f32_16x16x32_bf16 v[106:109], v[180:183], v[210:213], v[106:109]
	v_mfma_f32_16x16x32_bf16 v[98:101], v[188:191], v[210:213], v[98:101]
	v_mfma_f32_16x16x32_bf16 v[90:93], v[180:183], v[218:221], v[90:93]
	v_mfma_f32_16x16x32_bf16 v[82:85], v[188:191], v[218:221], v[82:85]
	v_mfma_f32_16x16x32_bf16 v[74:77], v[180:183], v[226:229], v[74:77]
	v_mfma_f32_16x16x32_bf16 v[66:69], v[188:191], v[226:229], v[66:69]
	s_setprio 0
	s_barrier
	s_mov_b32 m0, s44
	s_add_u32 s62, s22, 0x100000
	global_load_lds_dwordx4 v132, s[22:23]
	s_mov_b32 m0, s45
	s_addc_u32 s63, s23, 0
	global_load_lds_dwordx4 v136, s[22:23]
	s_mov_b32 m0, s46
	ds_read_b128 v[192:195], v150 offset:16384
	global_load_lds_dwordx4 v132, s[62:63]
	s_mov_b32 m0, s47
	ds_read_b128 v[202:205], v150 offset:17408
	global_load_lds_dwordx4 v136, s[62:63]
	s_mov_b32 m0, s31
	ds_read_b128 v[206:209], v150 offset:18432
	global_load_lds_dwordx4 v130, s[24:25]
	s_mov_b32 m0, s33
	ds_read_b128 v[210:213], v150 offset:19456
	global_load_lds_dwordx4 v134, s[24:25]
	ds_read_b128 v[214:217], v150 offset:20480
	ds_read_b128 v[218:221], v150 offset:21504
	ds_read_b128 v[222:225], v150 offset:22528
	ds_read_b128 v[226:229], v150 offset:23552
	s_waitcnt vmcnt(8)
	s_waitcnt lgkmcnt(0)
	s_barrier
	s_setprio 1
	s_waitcnt lgkmcnt(0)
	v_mfma_f32_16x16x32_bf16 v[62:65], v[142:145], v[192:195], v[62:65]
	v_mfma_f32_16x16x32_bf16 v[54:57], v[158:161], v[192:195], v[54:57]
	v_mfma_f32_16x16x32_bf16 v[46:49], v[142:145], v[206:209], v[46:49]
	v_mfma_f32_16x16x32_bf16 v[38:41], v[158:161], v[206:209], v[38:41]
	v_mfma_f32_16x16x32_bf16 v[30:33], v[142:145], v[214:217], v[30:33]
	v_mfma_f32_16x16x32_bf16 v[22:25], v[158:161], v[214:217], v[22:25]
	v_mfma_f32_16x16x32_bf16 v[14:17], v[142:145], v[222:225], v[14:17]
	v_mfma_f32_16x16x32_bf16 v[6:9], v[158:161], v[222:225], v[6:9]
	v_mfma_f32_16x16x32_bf16 v[62:65], v[154:157], v[202:205], v[62:65]
	v_mfma_f32_16x16x32_bf16 v[54:57], v[168:171], v[202:205], v[54:57]
	v_mfma_f32_16x16x32_bf16 v[46:49], v[154:157], v[210:213], v[46:49]
	v_mfma_f32_16x16x32_bf16 v[38:41], v[168:171], v[210:213], v[38:41]
	v_mfma_f32_16x16x32_bf16 v[30:33], v[154:157], v[218:221], v[30:33]
	v_mfma_f32_16x16x32_bf16 v[22:25], v[168:171], v[218:221], v[22:25]
	v_mfma_f32_16x16x32_bf16 v[14:17], v[154:157], v[226:229], v[14:17]
	v_mfma_f32_16x16x32_bf16 v[6:9], v[168:171], v[226:229], v[6:9]
	s_setprio 0
	s_setprio 1
	v_mfma_f32_16x16x32_bf16 v[58:61], v[176:179], v[192:195], v[58:61]
	v_mfma_f32_16x16x32_bf16 v[50:53], v[184:187], v[192:195], v[50:53]
	v_mfma_f32_16x16x32_bf16 v[42:45], v[176:179], v[206:209], v[42:45]
	v_mfma_f32_16x16x32_bf16 v[34:37], v[184:187], v[206:209], v[34:37]
	v_mfma_f32_16x16x32_bf16 v[26:29], v[176:179], v[214:217], v[26:29]
	v_mfma_f32_16x16x32_bf16 v[18:21], v[184:187], v[214:217], v[18:21]
	v_mfma_f32_16x16x32_bf16 v[10:13], v[176:179], v[222:225], v[10:13]
	v_mfma_f32_16x16x32_bf16 v[2:5], v[184:187], v[222:225], v[2:5]
	v_mfma_f32_16x16x32_bf16 v[58:61], v[180:183], v[202:205], v[58:61]
	v_mfma_f32_16x16x32_bf16 v[50:53], v[188:191], v[202:205], v[50:53]
	v_mfma_f32_16x16x32_bf16 v[42:45], v[180:183], v[210:213], v[42:45]
	v_mfma_f32_16x16x32_bf16 v[34:37], v[188:191], v[210:213], v[34:37]
	v_mfma_f32_16x16x32_bf16 v[26:29], v[180:183], v[218:221], v[26:29]
	v_mfma_f32_16x16x32_bf16 v[18:21], v[188:191], v[218:221], v[18:21]
	v_mfma_f32_16x16x32_bf16 v[10:13], v[180:183], v[226:229], v[10:13]
	v_mfma_f32_16x16x32_bf16 v[2:5], v[188:191], v[226:229], v[2:5]
	s_setprio 0
	s_barrier
	s_add_u32 s24, s24, 0x100000
	s_addc_u32 s25, s25, 0
	s_mov_b32 m0, s34
	ds_read_b128 v[142:145], v151
	global_load_lds_dwordx4 v130, s[24:25]
	s_mov_b32 m0, s35
	ds_read_b128 v[154:157], v151 offset:1024
	global_load_lds_dwordx4 v134, s[24:25]
	ds_read_b128 v[158:161], v151 offset:2048
	ds_read_b128 v[168:171], v151 offset:3072
	ds_read_b128 v[176:179], v152
	ds_read_b128 v[180:183], v152 offset:1024
	ds_read_b128 v[184:187], v152 offset:2048
	ds_read_b128 v[188:191], v152 offset:3072
	ds_read_b128 v[192:195], v150 offset:32768
	ds_read_b128 v[202:205], v150 offset:33792
	ds_read_b128 v[206:209], v150 offset:34816
	ds_read_b128 v[210:213], v150 offset:35840
	ds_read_b128 v[214:217], v150 offset:36864
	ds_read_b128 v[218:221], v150 offset:37888
	ds_read_b128 v[222:225], v150 offset:38912
	ds_read_b128 v[226:229], v150 offset:39936
	s_waitcnt vmcnt(8)
	s_waitcnt lgkmcnt(0)
	s_barrier
	s_setprio 1
	s_waitcnt lgkmcnt(0)
	v_mfma_f32_16x16x32_bf16 v[126:129], v[142:145], v[192:195], v[126:129]
	v_mfma_f32_16x16x32_bf16 v[118:121], v[158:161], v[192:195], v[118:121]
	v_mfma_f32_16x16x32_bf16 v[110:113], v[142:145], v[206:209], v[110:113]
	v_mfma_f32_16x16x32_bf16 v[102:105], v[158:161], v[206:209], v[102:105]
	v_mfma_f32_16x16x32_bf16 v[94:97], v[142:145], v[214:217], v[94:97]
	v_mfma_f32_16x16x32_bf16 v[86:89], v[158:161], v[214:217], v[86:89]
	v_mfma_f32_16x16x32_bf16 v[78:81], v[142:145], v[222:225], v[78:81]
	v_mfma_f32_16x16x32_bf16 v[70:73], v[158:161], v[222:225], v[70:73]
	v_mfma_f32_16x16x32_bf16 v[126:129], v[154:157], v[202:205], v[126:129]
	v_mfma_f32_16x16x32_bf16 v[118:121], v[168:171], v[202:205], v[118:121]
	v_mfma_f32_16x16x32_bf16 v[110:113], v[154:157], v[210:213], v[110:113]
	v_mfma_f32_16x16x32_bf16 v[102:105], v[168:171], v[210:213], v[102:105]
	v_mfma_f32_16x16x32_bf16 v[94:97], v[154:157], v[218:221], v[94:97]
	v_mfma_f32_16x16x32_bf16 v[86:89], v[168:171], v[218:221], v[86:89]
	v_mfma_f32_16x16x32_bf16 v[78:81], v[154:157], v[226:229], v[78:81]
	v_mfma_f32_16x16x32_bf16 v[70:73], v[168:171], v[226:229], v[70:73]
	s_setprio 0
	s_setprio 1
	v_mfma_f32_16x16x32_bf16 v[122:125], v[176:179], v[192:195], v[122:125]
	v_mfma_f32_16x16x32_bf16 v[114:117], v[184:187], v[192:195], v[114:117]
	v_mfma_f32_16x16x32_bf16 v[106:109], v[176:179], v[206:209], v[106:109]
	v_mfma_f32_16x16x32_bf16 v[98:101], v[184:187], v[206:209], v[98:101]
	v_mfma_f32_16x16x32_bf16 v[90:93], v[176:179], v[214:217], v[90:93]
	v_mfma_f32_16x16x32_bf16 v[82:85], v[184:187], v[214:217], v[82:85]
	v_mfma_f32_16x16x32_bf16 v[74:77], v[176:179], v[222:225], v[74:77]
	v_mfma_f32_16x16x32_bf16 v[66:69], v[184:187], v[222:225], v[66:69]
	v_mfma_f32_16x16x32_bf16 v[122:125], v[180:183], v[202:205], v[122:125]
	v_mfma_f32_16x16x32_bf16 v[114:117], v[188:191], v[202:205], v[114:117]
	v_mfma_f32_16x16x32_bf16 v[106:109], v[180:183], v[210:213], v[106:109]
	v_mfma_f32_16x16x32_bf16 v[98:101], v[188:191], v[210:213], v[98:101]
	v_mfma_f32_16x16x32_bf16 v[90:93], v[180:183], v[218:221], v[90:93]
	v_mfma_f32_16x16x32_bf16 v[82:85], v[188:191], v[218:221], v[82:85]
	v_mfma_f32_16x16x32_bf16 v[74:77], v[180:183], v[226:229], v[74:77]
	v_mfma_f32_16x16x32_bf16 v[66:69], v[188:191], v[226:229], v[66:69]
	s_setprio 0
	s_barrier
	s_mov_b32 m0, s48
	s_add_u32 s22, s22, 0x80
	s_addc_u32 s23, s23, 0
	global_load_lds_dwordx4 v132, s[22:23]
	s_mov_b32 m0, s49
	s_add_u32 s62, s24, 0xfff00080
	s_addc_u32 s63, s25, -1
	global_load_lds_dwordx4 v136, s[22:23]
	s_mov_b32 m0, s50
	s_add_u32 s22, s22, 0x100000
	s_addc_u32 s23, s23, 0
	global_load_lds_dwordx4 v132, s[22:23]
	s_mov_b32 m0, s51
	ds_read_b128 v[192:195], v150 offset:49152
	global_load_lds_dwordx4 v136, s[22:23]
	s_mov_b32 m0, s37
	ds_read_b128 v[202:205], v150 offset:50176
	global_load_lds_dwordx4 v130, s[62:63]
	s_mov_b32 m0, s38
	ds_read_b128 v[206:209], v150 offset:51200
	global_load_lds_dwordx4 v134, s[62:63]
	ds_read_b128 v[210:213], v150 offset:52224
	ds_read_b128 v[214:217], v150 offset:53248
	ds_read_b128 v[218:221], v150 offset:54272
	ds_read_b128 v[222:225], v150 offset:55296
	ds_read_b128 v[226:229], v150 offset:56320
	s_waitcnt vmcnt(8)
	s_waitcnt lgkmcnt(0)
	s_barrier
	s_setprio 1
	s_waitcnt lgkmcnt(0)
	v_mfma_f32_16x16x32_bf16 v[62:65], v[142:145], v[192:195], v[62:65]
	v_mfma_f32_16x16x32_bf16 v[54:57], v[158:161], v[192:195], v[54:57]
	v_mfma_f32_16x16x32_bf16 v[46:49], v[142:145], v[206:209], v[46:49]
	v_mfma_f32_16x16x32_bf16 v[38:41], v[158:161], v[206:209], v[38:41]
	v_mfma_f32_16x16x32_bf16 v[30:33], v[142:145], v[214:217], v[30:33]
	v_mfma_f32_16x16x32_bf16 v[22:25], v[158:161], v[214:217], v[22:25]
	v_mfma_f32_16x16x32_bf16 v[14:17], v[142:145], v[222:225], v[14:17]
	v_mfma_f32_16x16x32_bf16 v[6:9], v[158:161], v[222:225], v[6:9]
	v_mfma_f32_16x16x32_bf16 v[62:65], v[154:157], v[202:205], v[62:65]
	v_mfma_f32_16x16x32_bf16 v[54:57], v[168:171], v[202:205], v[54:57]
	v_mfma_f32_16x16x32_bf16 v[46:49], v[154:157], v[210:213], v[46:49]
	v_mfma_f32_16x16x32_bf16 v[38:41], v[168:171], v[210:213], v[38:41]
	v_mfma_f32_16x16x32_bf16 v[30:33], v[154:157], v[218:221], v[30:33]
	v_mfma_f32_16x16x32_bf16 v[22:25], v[168:171], v[218:221], v[22:25]
	v_mfma_f32_16x16x32_bf16 v[14:17], v[154:157], v[226:229], v[14:17]
	v_mfma_f32_16x16x32_bf16 v[6:9], v[168:171], v[226:229], v[6:9]
	s_setprio 0
	s_setprio 1
	v_mfma_f32_16x16x32_bf16 v[58:61], v[176:179], v[192:195], v[58:61]
	v_mfma_f32_16x16x32_bf16 v[50:53], v[184:187], v[192:195], v[50:53]
	v_mfma_f32_16x16x32_bf16 v[42:45], v[176:179], v[206:209], v[42:45]
	v_mfma_f32_16x16x32_bf16 v[34:37], v[184:187], v[206:209], v[34:37]
	v_mfma_f32_16x16x32_bf16 v[26:29], v[176:179], v[214:217], v[26:29]
	v_mfma_f32_16x16x32_bf16 v[18:21], v[184:187], v[214:217], v[18:21]
	v_mfma_f32_16x16x32_bf16 v[10:13], v[176:179], v[222:225], v[10:13]
	v_mfma_f32_16x16x32_bf16 v[2:5], v[184:187], v[222:225], v[2:5]
	v_mfma_f32_16x16x32_bf16 v[58:61], v[180:183], v[202:205], v[58:61]
	v_mfma_f32_16x16x32_bf16 v[50:53], v[188:191], v[202:205], v[50:53]
	v_mfma_f32_16x16x32_bf16 v[42:45], v[180:183], v[210:213], v[42:45]
	v_mfma_f32_16x16x32_bf16 v[34:37], v[188:191], v[210:213], v[34:37]
	v_mfma_f32_16x16x32_bf16 v[26:29], v[180:183], v[218:221], v[26:29]
	v_mfma_f32_16x16x32_bf16 v[18:21], v[188:191], v[218:221], v[18:21]
	v_mfma_f32_16x16x32_bf16 v[10:13], v[180:183], v[226:229], v[10:13]
	v_mfma_f32_16x16x32_bf16 v[2:5], v[188:191], v[226:229], v[2:5]
	s_setprio 0
	s_barrier
	s_add_i32 s61, s61, 2
	s_add_u32 s20, s20, 0x100
	s_addc_u32 s21, s21, 0
	s_add_u32 s57, s57, 0x100
	s_addc_u32 s60, s60, 0
	s_cmp_gt_u32 s61, 61
	s_cbranch_scc0 .LBB0_1172
	s_and_b64 vcc, exec, s[16:17]
	s_cbranch_vccz .LBB0_1175
	s_barrier

.LBB0_1418:
	s_mov_b32 m0, s42
	ds_read_b128 v[142:145], v156
	global_load_lds_dwordx4 v138, s[22:23]
	s_mov_b32 m0, s43
	ds_read_b128 v[168:171], v156 offset:1024
	global_load_lds_dwordx4 v140, s[22:23]
	ds_read_b128 v[176:179], v156 offset:2048
	ds_read_b128 v[180:183], v156 offset:3072
	ds_read_b128 v[184:187], v157
	ds_read_b128 v[188:191], v157 offset:1024
	ds_read_b128 v[192:195], v157 offset:2048
	ds_read_b128 v[204:207], v157 offset:3072
	s_add_u32 s24, s22, 0xffd50080
	s_addc_u32 s25, s23, -1
	s_cmpk_eq_i32 s55, 0xa8
	s_cselect_b32 s27, s19, s25
	s_cselect_b32 s26, s18, s24
	s_cselect_b32 s25, s17, s54
	s_cselect_b32 s24, s16, s53
	ds_read_b128 v[208:211], v158
	ds_read_b128 v[212:215], v158 offset:1024
	ds_read_b128 v[216:219], v158 offset:2048
	ds_read_b128 v[220:223], v158 offset:3072
	ds_read_b128 v[224:227], v158 offset:4096
	ds_read_b128 v[228:231], v158 offset:5120
	ds_read_b128 v[232:235], v158 offset:6144
	ds_read_b128 v[236:239], v158 offset:7168
	s_waitcnt vmcnt(8)
	s_waitcnt lgkmcnt(0)
	s_barrier
	s_setprio 1
	s_waitcnt lgkmcnt(0)
	v_mfma_f32_16x16x32_bf16 v[126:129], v[142:145], v[208:211], v[126:129]
	v_mfma_f32_16x16x32_bf16 v[122:125], v[176:179], v[208:211], v[122:125]
	v_mfma_f32_16x16x32_bf16 v[110:113], v[142:145], v[216:219], v[110:113]
	v_mfma_f32_16x16x32_bf16 v[106:109], v[176:179], v[216:219], v[106:109]
	v_mfma_f32_16x16x32_bf16 v[94:97], v[142:145], v[224:227], v[94:97]
	v_mfma_f32_16x16x32_bf16 v[90:93], v[176:179], v[224:227], v[90:93]
	v_mfma_f32_16x16x32_bf16 v[78:81], v[142:145], v[232:235], v[78:81]
	v_mfma_f32_16x16x32_bf16 v[74:77], v[176:179], v[232:235], v[74:77]
	v_mfma_f32_16x16x32_bf16 v[126:129], v[168:171], v[212:215], v[126:129]
	v_mfma_f32_16x16x32_bf16 v[122:125], v[180:183], v[212:215], v[122:125]
	v_mfma_f32_16x16x32_bf16 v[110:113], v[168:171], v[220:223], v[110:113]
	v_mfma_f32_16x16x32_bf16 v[106:109], v[180:183], v[220:223], v[106:109]
	v_mfma_f32_16x16x32_bf16 v[94:97], v[168:171], v[228:231], v[94:97]
	v_mfma_f32_16x16x32_bf16 v[90:93], v[180:183], v[228:231], v[90:93]
	v_mfma_f32_16x16x32_bf16 v[78:81], v[168:171], v[236:239], v[78:81]
	v_mfma_f32_16x16x32_bf16 v[74:77], v[180:183], v[236:239], v[74:77]
	s_setprio 0
	s_setprio 1
	v_mfma_f32_16x16x32_bf16 v[118:121], v[184:187], v[208:211], v[118:121]
	v_mfma_f32_16x16x32_bf16 v[114:117], v[192:195], v[208:211], v[114:117]
	v_mfma_f32_16x16x32_bf16 v[102:105], v[184:187], v[216:219], v[102:105]
	v_mfma_f32_16x16x32_bf16 v[98:101], v[192:195], v[216:219], v[98:101]
	v_mfma_f32_16x16x32_bf16 v[86:89], v[184:187], v[224:227], v[86:89]
	v_mfma_f32_16x16x32_bf16 v[82:85], v[192:195], v[224:227], v[82:85]
	v_mfma_f32_16x16x32_bf16 v[70:73], v[184:187], v[232:235], v[70:73]
	v_mfma_f32_16x16x32_bf16 v[66:69], v[192:195], v[232:235], v[66:69]
	v_mfma_f32_16x16x32_bf16 v[118:121], v[188:191], v[212:215], v[118:121]
	v_mfma_f32_16x16x32_bf16 v[114:117], v[204:207], v[212:215], v[114:117]
	v_mfma_f32_16x16x32_bf16 v[102:105], v[188:191], v[220:223], v[102:105]
	v_mfma_f32_16x16x32_bf16 v[98:101], v[204:207], v[220:223], v[98:101]
	v_mfma_f32_16x16x32_bf16 v[86:89], v[188:191], v[228:231], v[86:89]
	v_mfma_f32_16x16x32_bf16 v[82:85], v[204:207], v[228:231], v[82:85]
	v_mfma_f32_16x16x32_bf16 v[70:73], v[188:191], v[236:239], v[70:73]
	v_mfma_f32_16x16x32_bf16 v[66:69], v[204:207], v[236:239], v[66:69]
	s_setprio 0
	s_barrier
	s_mov_b32 m0, s44
	s_add_u32 s56, s24, 0x2b0000
	global_load_lds_dwordx4 v132, s[24:25]
	s_mov_b32 m0, s45
	s_addc_u32 s57, s25, 0
	global_load_lds_dwordx4 v136, s[24:25]
	s_mov_b32 m0, s46
	ds_read_b128 v[208:211], v158 offset:16384
	global_load_lds_dwordx4 v132, s[56:57]
	s_mov_b32 m0, s47
	ds_read_b128 v[212:215], v158 offset:17408
	global_load_lds_dwordx4 v136, s[56:57]
	s_mov_b32 m0, s35
	ds_read_b128 v[216:219], v158 offset:18432
	global_load_lds_dwordx4 v130, s[26:27]
	s_mov_b32 m0, s36
	ds_read_b128 v[220:223], v158 offset:19456
	global_load_lds_dwordx4 v134, s[26:27]
	ds_read_b128 v[224:227], v158 offset:20480
	ds_read_b128 v[228:231], v158 offset:21504
	ds_read_b128 v[232:235], v158 offset:22528
	ds_read_b128 v[236:239], v158 offset:23552
	s_waitcnt vmcnt(8)
	s_waitcnt lgkmcnt(0)
	s_barrier
	s_setprio 1
	s_waitcnt lgkmcnt(0)
	v_mfma_f32_16x16x32_bf16 v[62:65], v[142:145], v[208:211], v[62:65]
	v_mfma_f32_16x16x32_bf16 v[58:61], v[176:179], v[208:211], v[58:61]
	v_mfma_f32_16x16x32_bf16 v[46:49], v[142:145], v[216:219], v[46:49]
	v_mfma_f32_16x16x32_bf16 v[42:45], v[176:179], v[216:219], v[42:45]
	v_mfma_f32_16x16x32_bf16 v[30:33], v[142:145], v[224:227], v[30:33]
	v_mfma_f32_16x16x32_bf16 v[26:29], v[176:179], v[224:227], v[26:29]
	v_mfma_f32_16x16x32_bf16 v[14:17], v[142:145], v[232:235], v[14:17]
	v_mfma_f32_16x16x32_bf16 v[10:13], v[176:179], v[232:235], v[10:13]
	v_mfma_f32_16x16x32_bf16 v[62:65], v[168:171], v[212:215], v[62:65]
	v_mfma_f32_16x16x32_bf16 v[58:61], v[180:183], v[212:215], v[58:61]
	v_mfma_f32_16x16x32_bf16 v[46:49], v[168:171], v[220:223], v[46:49]
	v_mfma_f32_16x16x32_bf16 v[42:45], v[180:183], v[220:223], v[42:45]
	v_mfma_f32_16x16x32_bf16 v[30:33], v[168:171], v[228:231], v[30:33]
	v_mfma_f32_16x16x32_bf16 v[26:29], v[180:183], v[228:231], v[26:29]
	v_mfma_f32_16x16x32_bf16 v[14:17], v[168:171], v[236:239], v[14:17]
	v_mfma_f32_16x16x32_bf16 v[10:13], v[180:183], v[236:239], v[10:13]
	s_setprio 0
	s_setprio 1
	v_mfma_f32_16x16x32_bf16 v[54:57], v[184:187], v[208:211], v[54:57]
	v_mfma_f32_16x16x32_bf16 v[50:53], v[192:195], v[208:211], v[50:53]
	v_mfma_f32_16x16x32_bf16 v[38:41], v[184:187], v[216:219], v[38:41]
	v_mfma_f32_16x16x32_bf16 v[34:37], v[192:195], v[216:219], v[34:37]
	v_mfma_f32_16x16x32_bf16 v[22:25], v[184:187], v[224:227], v[22:25]
	v_mfma_f32_16x16x32_bf16 v[18:21], v[192:195], v[224:227], v[18:21]
	v_mfma_f32_16x16x32_bf16 v[6:9], v[184:187], v[232:235], v[6:9]
	v_mfma_f32_16x16x32_bf16 v[2:5], v[192:195], v[232:235], v[2:5]
	v_mfma_f32_16x16x32_bf16 v[54:57], v[188:191], v[212:215], v[54:57]
	v_mfma_f32_16x16x32_bf16 v[50:53], v[204:207], v[212:215], v[50:53]
	v_mfma_f32_16x16x32_bf16 v[38:41], v[188:191], v[220:223], v[38:41]
	v_mfma_f32_16x16x32_bf16 v[34:37], v[204:207], v[220:223], v[34:37]
	v_mfma_f32_16x16x32_bf16 v[22:25], v[188:191], v[228:231], v[22:25]
	v_mfma_f32_16x16x32_bf16 v[18:21], v[204:207], v[228:231], v[18:21]
	v_mfma_f32_16x16x32_bf16 v[6:9], v[188:191], v[236:239], v[6:9]
	v_mfma_f32_16x16x32_bf16 v[2:5], v[204:207], v[236:239], v[2:5]
	s_setprio 0
	s_barrier
	s_add_u32 s26, s26, 0x2b0000
	s_addc_u32 s27, s27, 0
	s_mov_b32 m0, s37
	ds_read_b128 v[142:145], v159
	global_load_lds_dwordx4 v130, s[26:27]
	s_mov_b32 m0, s38
	ds_read_b128 v[168:171], v159 offset:1024
	global_load_lds_dwordx4 v134, s[26:27]
	ds_read_b128 v[176:179], v159 offset:2048
	ds_read_b128 v[180:183], v159 offset:3072
	ds_read_b128 v[184:187], v160
	ds_read_b128 v[188:191], v160 offset:1024
	ds_read_b128 v[192:195], v160 offset:2048
	ds_read_b128 v[204:207], v160 offset:3072
	ds_read_b128 v[208:211], v158 offset:32768
	ds_read_b128 v[212:215], v158 offset:33792
	ds_read_b128 v[216:219], v158 offset:34816
	ds_read_b128 v[220:223], v158 offset:35840
	ds_read_b128 v[224:227], v158 offset:36864
	ds_read_b128 v[228:231], v158 offset:37888
	ds_read_b128 v[232:235], v158 offset:38912
	ds_read_b128 v[236:239], v158 offset:39936
	s_waitcnt vmcnt(8)
	s_waitcnt lgkmcnt(0)
	s_barrier
	s_setprio 1
	s_waitcnt lgkmcnt(0)
	v_mfma_f32_16x16x32_bf16 v[126:129], v[142:145], v[208:211], v[126:129]
	v_mfma_f32_16x16x32_bf16 v[122:125], v[176:179], v[208:211], v[122:125]
	v_mfma_f32_16x16x32_bf16 v[110:113], v[142:145], v[216:219], v[110:113]
	v_mfma_f32_16x16x32_bf16 v[106:109], v[176:179], v[216:219], v[106:109]
	v_mfma_f32_16x16x32_bf16 v[94:97], v[142:145], v[224:227], v[94:97]
	v_mfma_f32_16x16x32_bf16 v[90:93], v[176:179], v[224:227], v[90:93]
	v_mfma_f32_16x16x32_bf16 v[78:81], v[142:145], v[232:235], v[78:81]
	v_mfma_f32_16x16x32_bf16 v[74:77], v[176:179], v[232:235], v[74:77]
	v_mfma_f32_16x16x32_bf16 v[126:129], v[168:171], v[212:215], v[126:129]
	v_mfma_f32_16x16x32_bf16 v[122:125], v[180:183], v[212:215], v[122:125]
	v_mfma_f32_16x16x32_bf16 v[110:113], v[168:171], v[220:223], v[110:113]
	v_mfma_f32_16x16x32_bf16 v[106:109], v[180:183], v[220:223], v[106:109]
	v_mfma_f32_16x16x32_bf16 v[94:97], v[168:171], v[228:231], v[94:97]
	v_mfma_f32_16x16x32_bf16 v[90:93], v[180:183], v[228:231], v[90:93]
	v_mfma_f32_16x16x32_bf16 v[78:81], v[168:171], v[236:239], v[78:81]
	v_mfma_f32_16x16x32_bf16 v[74:77], v[180:183], v[236:239], v[74:77]
	s_setprio 0
	s_setprio 1
	v_mfma_f32_16x16x32_bf16 v[118:121], v[184:187], v[208:211], v[118:121]
	v_mfma_f32_16x16x32_bf16 v[114:117], v[192:195], v[208:211], v[114:117]
	v_mfma_f32_16x16x32_bf16 v[102:105], v[184:187], v[216:219], v[102:105]
	v_mfma_f32_16x16x32_bf16 v[98:101], v[192:195], v[216:219], v[98:101]
	v_mfma_f32_16x16x32_bf16 v[86:89], v[184:187], v[224:227], v[86:89]
	v_mfma_f32_16x16x32_bf16 v[82:85], v[192:195], v[224:227], v[82:85]
	v_mfma_f32_16x16x32_bf16 v[70:73], v[184:187], v[232:235], v[70:73]
	v_mfma_f32_16x16x32_bf16 v[66:69], v[192:195], v[232:235], v[66:69]
	v_mfma_f32_16x16x32_bf16 v[118:121], v[188:191], v[212:215], v[118:121]
	v_mfma_f32_16x16x32_bf16 v[114:117], v[204:207], v[212:215], v[114:117]
	v_mfma_f32_16x16x32_bf16 v[102:105], v[188:191], v[220:223], v[102:105]
	v_mfma_f32_16x16x32_bf16 v[98:101], v[204:207], v[220:223], v[98:101]
	v_mfma_f32_16x16x32_bf16 v[86:89], v[188:191], v[228:231], v[86:89]
	v_mfma_f32_16x16x32_bf16 v[82:85], v[204:207], v[228:231], v[82:85]
	v_mfma_f32_16x16x32_bf16 v[70:73], v[188:191], v[236:239], v[70:73]
	v_mfma_f32_16x16x32_bf16 v[66:69], v[204:207], v[236:239], v[66:69]
	s_setprio 0
	s_barrier
	s_mov_b32 m0, s48
	s_add_u32 s24, s24, 0x80
	s_addc_u32 s25, s25, 0
	global_load_lds_dwordx4 v132, s[24:25]
	s_mov_b32 m0, s49
	s_add_u32 s56, s26, 0xffd50080
	s_addc_u32 s57, s27, -1
	global_load_lds_dwordx4 v136, s[24:25]
	s_mov_b32 m0, s50
	s_add_u32 s24, s24, 0x2b0000
	s_addc_u32 s25, s25, 0
	global_load_lds_dwordx4 v132, s[24:25]
	s_add_i32 m0, s50, 0x2000
	ds_read_b128 v[208:211], v158 offset:49152
	global_load_lds_dwordx4 v136, s[24:25]
	s_mov_b32 m0, s40
	ds_read_b128 v[212:215], v158 offset:50176
	global_load_lds_dwordx4 v130, s[56:57]
	s_mov_b32 m0, s41
	ds_read_b128 v[216:219], v158 offset:51200
	global_load_lds_dwordx4 v134, s[56:57]
	ds_read_b128 v[220:223], v158 offset:52224
	ds_read_b128 v[224:227], v158 offset:53248
	ds_read_b128 v[228:231], v158 offset:54272
	ds_read_b128 v[232:235], v158 offset:55296
	ds_read_b128 v[236:239], v158 offset:56320
	s_waitcnt vmcnt(8)
	s_waitcnt lgkmcnt(0)
	s_barrier
	s_setprio 1
	s_waitcnt lgkmcnt(0)
	v_mfma_f32_16x16x32_bf16 v[62:65], v[142:145], v[208:211], v[62:65]
	v_mfma_f32_16x16x32_bf16 v[58:61], v[176:179], v[208:211], v[58:61]
	v_mfma_f32_16x16x32_bf16 v[46:49], v[142:145], v[216:219], v[46:49]
	v_mfma_f32_16x16x32_bf16 v[42:45], v[176:179], v[216:219], v[42:45]
	v_mfma_f32_16x16x32_bf16 v[30:33], v[142:145], v[224:227], v[30:33]
	v_mfma_f32_16x16x32_bf16 v[26:29], v[176:179], v[224:227], v[26:29]
	v_mfma_f32_16x16x32_bf16 v[14:17], v[142:145], v[232:235], v[14:17]
	v_mfma_f32_16x16x32_bf16 v[10:13], v[176:179], v[232:235], v[10:13]
	v_mfma_f32_16x16x32_bf16 v[62:65], v[168:171], v[212:215], v[62:65]
	v_mfma_f32_16x16x32_bf16 v[58:61], v[180:183], v[212:215], v[58:61]
	v_mfma_f32_16x16x32_bf16 v[46:49], v[168:171], v[220:223], v[46:49]
	v_mfma_f32_16x16x32_bf16 v[42:45], v[180:183], v[220:223], v[42:45]
	v_mfma_f32_16x16x32_bf16 v[30:33], v[168:171], v[228:231], v[30:33]
	v_mfma_f32_16x16x32_bf16 v[26:29], v[180:183], v[228:231], v[26:29]
	v_mfma_f32_16x16x32_bf16 v[14:17], v[168:171], v[236:239], v[14:17]
	v_mfma_f32_16x16x32_bf16 v[10:13], v[180:183], v[236:239], v[10:13]
	s_setprio 0
	s_setprio 1
	v_mfma_f32_16x16x32_bf16 v[54:57], v[184:187], v[208:211], v[54:57]
	v_mfma_f32_16x16x32_bf16 v[50:53], v[192:195], v[208:211], v[50:53]
	v_mfma_f32_16x16x32_bf16 v[38:41], v[184:187], v[216:219], v[38:41]
	v_mfma_f32_16x16x32_bf16 v[34:37], v[192:195], v[216:219], v[34:37]
	v_mfma_f32_16x16x32_bf16 v[22:25], v[184:187], v[224:227], v[22:25]
	v_mfma_f32_16x16x32_bf16 v[18:21], v[192:195], v[224:227], v[18:21]
	v_mfma_f32_16x16x32_bf16 v[6:9], v[184:187], v[232:235], v[6:9]
	v_mfma_f32_16x16x32_bf16 v[2:5], v[192:195], v[232:235], v[2:5]
	v_mfma_f32_16x16x32_bf16 v[54:57], v[188:191], v[212:215], v[54:57]
	v_mfma_f32_16x16x32_bf16 v[50:53], v[204:207], v[212:215], v[50:53]
	v_mfma_f32_16x16x32_bf16 v[38:41], v[188:191], v[220:223], v[38:41]
	v_mfma_f32_16x16x32_bf16 v[34:37], v[204:207], v[220:223], v[34:37]
	v_mfma_f32_16x16x32_bf16 v[22:25], v[188:191], v[228:231], v[22:25]
	v_mfma_f32_16x16x32_bf16 v[18:21], v[204:207], v[228:231], v[18:21]
	v_mfma_f32_16x16x32_bf16 v[6:9], v[188:191], v[236:239], v[6:9]
	v_mfma_f32_16x16x32_bf16 v[2:5], v[204:207], v[236:239], v[2:5]
	s_setprio 0
	s_barrier
	s_add_i32 s55, s55, 2
	s_add_u32 s22, s22, 0x100
	s_addc_u32 s23, s23, 0
	s_add_u32 s53, s53, 0x100
	s_addc_u32 s54, s54, 0
	s_cmpk_gt_u32 s55, 0xa9
	s_cbranch_scc0 .LBB0_1418
	s_and_b64 vcc, exec, s[14:15]
	s_cbranch_vccz .LBB0_1421
	s_barrier

.LBB0_2373:
	s_mov_b32 m0, s40
	ds_read_b128 v[142:145], v148
	global_load_lds_dwordx4 v138, s[20:21]
	s_mov_b32 m0, s41
	ds_read_b128 v[154:157], v148 offset:1024
	global_load_lds_dwordx4 v140, s[20:21]
	ds_read_b128 v[158:161], v148 offset:2048
	ds_read_b128 v[168:171], v148 offset:3072
	ds_read_b128 v[176:179], v149
	ds_read_b128 v[180:183], v149 offset:1024
	ds_read_b128 v[184:187], v149 offset:2048
	ds_read_b128 v[188:191], v149 offset:3072
	s_add_u32 s22, s20, 0xfff00080
	s_addc_u32 s23, s21, -1
	s_cmp_eq_u32 s57, 60
	s_cselect_b32 s25, s52, s23
	s_cselect_b32 s24, s53, s22
	s_cselect_b32 s23, s7, s56
	s_cselect_b32 s22, s54, s55
	ds_read_b128 v[192:195], v150
	ds_read_b128 v[204:207], v150 offset:1024
	ds_read_b128 v[208:211], v150 offset:2048
	ds_read_b128 v[212:215], v150 offset:3072
	ds_read_b128 v[216:219], v150 offset:4096
	ds_read_b128 v[220:223], v150 offset:5120
	ds_read_b128 v[224:227], v150 offset:6144
	ds_read_b128 v[228:231], v150 offset:7168
	s_waitcnt vmcnt(8)
	s_waitcnt lgkmcnt(0)
	s_barrier
	s_setprio 1
	s_waitcnt lgkmcnt(0)
	v_mfma_f32_16x16x32_bf16 v[126:129], v[142:145], v[192:195], v[126:129]
	v_mfma_f32_16x16x32_bf16 v[122:125], v[158:161], v[192:195], v[122:125]
	v_mfma_f32_16x16x32_bf16 v[110:113], v[142:145], v[208:211], v[110:113]
	v_mfma_f32_16x16x32_bf16 v[106:109], v[158:161], v[208:211], v[106:109]
	v_mfma_f32_16x16x32_bf16 v[94:97], v[142:145], v[216:219], v[94:97]
	v_mfma_f32_16x16x32_bf16 v[90:93], v[158:161], v[216:219], v[90:93]
	v_mfma_f32_16x16x32_bf16 v[78:81], v[142:145], v[224:227], v[78:81]
	v_mfma_f32_16x16x32_bf16 v[74:77], v[158:161], v[224:227], v[74:77]
	v_mfma_f32_16x16x32_bf16 v[126:129], v[154:157], v[204:207], v[126:129]
	v_mfma_f32_16x16x32_bf16 v[122:125], v[168:171], v[204:207], v[122:125]
	v_mfma_f32_16x16x32_bf16 v[110:113], v[154:157], v[212:215], v[110:113]
	v_mfma_f32_16x16x32_bf16 v[106:109], v[168:171], v[212:215], v[106:109]
	v_mfma_f32_16x16x32_bf16 v[94:97], v[154:157], v[220:223], v[94:97]
	v_mfma_f32_16x16x32_bf16 v[90:93], v[168:171], v[220:223], v[90:93]
	v_mfma_f32_16x16x32_bf16 v[78:81], v[154:157], v[228:231], v[78:81]
	v_mfma_f32_16x16x32_bf16 v[74:77], v[168:171], v[228:231], v[74:77]
	s_setprio 0
	s_setprio 1
	v_mfma_f32_16x16x32_bf16 v[118:121], v[176:179], v[192:195], v[118:121]
	v_mfma_f32_16x16x32_bf16 v[114:117], v[184:187], v[192:195], v[114:117]
	v_mfma_f32_16x16x32_bf16 v[102:105], v[176:179], v[208:211], v[102:105]
	v_mfma_f32_16x16x32_bf16 v[98:101], v[184:187], v[208:211], v[98:101]
	v_mfma_f32_16x16x32_bf16 v[86:89], v[176:179], v[216:219], v[86:89]
	v_mfma_f32_16x16x32_bf16 v[82:85], v[184:187], v[216:219], v[82:85]
	v_mfma_f32_16x16x32_bf16 v[70:73], v[176:179], v[224:227], v[70:73]
	v_mfma_f32_16x16x32_bf16 v[66:69], v[184:187], v[224:227], v[66:69]
	v_mfma_f32_16x16x32_bf16 v[118:121], v[180:183], v[204:207], v[118:121]
	v_mfma_f32_16x16x32_bf16 v[114:117], v[188:191], v[204:207], v[114:117]
	v_mfma_f32_16x16x32_bf16 v[102:105], v[180:183], v[212:215], v[102:105]
	v_mfma_f32_16x16x32_bf16 v[98:101], v[188:191], v[212:215], v[98:101]
	v_mfma_f32_16x16x32_bf16 v[86:89], v[180:183], v[220:223], v[86:89]
	v_mfma_f32_16x16x32_bf16 v[82:85], v[188:191], v[220:223], v[82:85]
	v_mfma_f32_16x16x32_bf16 v[70:73], v[180:183], v[228:231], v[70:73]
	v_mfma_f32_16x16x32_bf16 v[66:69], v[188:191], v[228:231], v[66:69]
	s_setprio 0
	s_barrier
	s_mov_b32 m0, s42
	s_add_u32 s60, s22, 0x100000
	global_load_lds_dwordx4 v132, s[22:23]
	s_mov_b32 m0, s43
	s_addc_u32 s61, s23, 0
	global_load_lds_dwordx4 v136, s[22:23]
	s_mov_b32 m0, s44
	ds_read_b128 v[192:195], v150 offset:16384
	global_load_lds_dwordx4 v132, s[60:61]
	s_mov_b32 m0, s45
	ds_read_b128 v[204:207], v150 offset:17408
	global_load_lds_dwordx4 v136, s[60:61]
	s_mov_b32 m0, s29
	ds_read_b128 v[208:211], v150 offset:18432
	global_load_lds_dwordx4 v130, s[24:25]
	s_mov_b32 m0, s30
	ds_read_b128 v[212:215], v150 offset:19456
	global_load_lds_dwordx4 v134, s[24:25]
	ds_read_b128 v[216:219], v150 offset:20480
	ds_read_b128 v[220:223], v150 offset:21504
	ds_read_b128 v[224:227], v150 offset:22528
	ds_read_b128 v[228:231], v150 offset:23552
	s_waitcnt vmcnt(8)
	s_waitcnt lgkmcnt(0)
	s_barrier
	s_setprio 1
	s_waitcnt lgkmcnt(0)
	v_mfma_f32_16x16x32_bf16 v[62:65], v[142:145], v[192:195], v[62:65]
	v_mfma_f32_16x16x32_bf16 v[58:61], v[158:161], v[192:195], v[58:61]
	v_mfma_f32_16x16x32_bf16 v[46:49], v[142:145], v[208:211], v[46:49]
	v_mfma_f32_16x16x32_bf16 v[42:45], v[158:161], v[208:211], v[42:45]
	v_mfma_f32_16x16x32_bf16 v[30:33], v[142:145], v[216:219], v[30:33]
	v_mfma_f32_16x16x32_bf16 v[26:29], v[158:161], v[216:219], v[26:29]
	v_mfma_f32_16x16x32_bf16 v[14:17], v[142:145], v[224:227], v[14:17]
	v_mfma_f32_16x16x32_bf16 v[10:13], v[158:161], v[224:227], v[10:13]
	v_mfma_f32_16x16x32_bf16 v[62:65], v[154:157], v[204:207], v[62:65]
	v_mfma_f32_16x16x32_bf16 v[58:61], v[168:171], v[204:207], v[58:61]
	v_mfma_f32_16x16x32_bf16 v[46:49], v[154:157], v[212:215], v[46:49]
	v_mfma_f32_16x16x32_bf16 v[42:45], v[168:171], v[212:215], v[42:45]
	v_mfma_f32_16x16x32_bf16 v[30:33], v[154:157], v[220:223], v[30:33]
	v_mfma_f32_16x16x32_bf16 v[26:29], v[168:171], v[220:223], v[26:29]
	v_mfma_f32_16x16x32_bf16 v[14:17], v[154:157], v[228:231], v[14:17]
	v_mfma_f32_16x16x32_bf16 v[10:13], v[168:171], v[228:231], v[10:13]
	s_setprio 0
	s_setprio 1
	v_mfma_f32_16x16x32_bf16 v[54:57], v[176:179], v[192:195], v[54:57]
	v_mfma_f32_16x16x32_bf16 v[50:53], v[184:187], v[192:195], v[50:53]
	v_mfma_f32_16x16x32_bf16 v[38:41], v[176:179], v[208:211], v[38:41]
	v_mfma_f32_16x16x32_bf16 v[34:37], v[184:187], v[208:211], v[34:37]
	v_mfma_f32_16x16x32_bf16 v[22:25], v[176:179], v[216:219], v[22:25]
	v_mfma_f32_16x16x32_bf16 v[18:21], v[184:187], v[216:219], v[18:21]
	v_mfma_f32_16x16x32_bf16 v[6:9], v[176:179], v[224:227], v[6:9]
	v_mfma_f32_16x16x32_bf16 v[2:5], v[184:187], v[224:227], v[2:5]
	v_mfma_f32_16x16x32_bf16 v[54:57], v[180:183], v[204:207], v[54:57]
	v_mfma_f32_16x16x32_bf16 v[50:53], v[188:191], v[204:207], v[50:53]
	v_mfma_f32_16x16x32_bf16 v[38:41], v[180:183], v[212:215], v[38:41]
	v_mfma_f32_16x16x32_bf16 v[34:37], v[188:191], v[212:215], v[34:37]
	v_mfma_f32_16x16x32_bf16 v[22:25], v[180:183], v[220:223], v[22:25]
	v_mfma_f32_16x16x32_bf16 v[18:21], v[188:191], v[220:223], v[18:21]
	v_mfma_f32_16x16x32_bf16 v[6:9], v[180:183], v[228:231], v[6:9]
	v_mfma_f32_16x16x32_bf16 v[2:5], v[188:191], v[228:231], v[2:5]
	s_setprio 0
	s_barrier
	s_add_u32 s24, s24, 0x100000
	s_addc_u32 s25, s25, 0
	s_mov_b32 m0, s31
	ds_read_b128 v[142:145], v151
	global_load_lds_dwordx4 v130, s[24:25]
	s_mov_b32 m0, s33
	ds_read_b128 v[154:157], v151 offset:1024
	global_load_lds_dwordx4 v134, s[24:25]
	ds_read_b128 v[158:161], v151 offset:2048
	ds_read_b128 v[168:171], v151 offset:3072
	ds_read_b128 v[176:179], v152
	ds_read_b128 v[180:183], v152 offset:1024
	ds_read_b128 v[184:187], v152 offset:2048
	ds_read_b128 v[188:191], v152 offset:3072
	ds_read_b128 v[192:195], v150 offset:32768
	ds_read_b128 v[204:207], v150 offset:33792
	ds_read_b128 v[208:211], v150 offset:34816
	ds_read_b128 v[212:215], v150 offset:35840
	ds_read_b128 v[216:219], v150 offset:36864
	ds_read_b128 v[220:223], v150 offset:37888
	ds_read_b128 v[224:227], v150 offset:38912
	ds_read_b128 v[228:231], v150 offset:39936
	s_waitcnt vmcnt(8)
	s_waitcnt lgkmcnt(0)
	s_barrier
	s_setprio 1
	s_waitcnt lgkmcnt(0)
	v_mfma_f32_16x16x32_bf16 v[126:129], v[142:145], v[192:195], v[126:129]
	v_mfma_f32_16x16x32_bf16 v[122:125], v[158:161], v[192:195], v[122:125]
	v_mfma_f32_16x16x32_bf16 v[110:113], v[142:145], v[208:211], v[110:113]
	v_mfma_f32_16x16x32_bf16 v[106:109], v[158:161], v[208:211], v[106:109]
	v_mfma_f32_16x16x32_bf16 v[94:97], v[142:145], v[216:219], v[94:97]
	v_mfma_f32_16x16x32_bf16 v[90:93], v[158:161], v[216:219], v[90:93]
	v_mfma_f32_16x16x32_bf16 v[78:81], v[142:145], v[224:227], v[78:81]
	v_mfma_f32_16x16x32_bf16 v[74:77], v[158:161], v[224:227], v[74:77]
	v_mfma_f32_16x16x32_bf16 v[126:129], v[154:157], v[204:207], v[126:129]
	v_mfma_f32_16x16x32_bf16 v[122:125], v[168:171], v[204:207], v[122:125]
	v_mfma_f32_16x16x32_bf16 v[110:113], v[154:157], v[212:215], v[110:113]
	v_mfma_f32_16x16x32_bf16 v[106:109], v[168:171], v[212:215], v[106:109]
	v_mfma_f32_16x16x32_bf16 v[94:97], v[154:157], v[220:223], v[94:97]
	v_mfma_f32_16x16x32_bf16 v[90:93], v[168:171], v[220:223], v[90:93]
	v_mfma_f32_16x16x32_bf16 v[78:81], v[154:157], v[228:231], v[78:81]
	v_mfma_f32_16x16x32_bf16 v[74:77], v[168:171], v[228:231], v[74:77]
	s_setprio 0
	s_setprio 1
	v_mfma_f32_16x16x32_bf16 v[118:121], v[176:179], v[192:195], v[118:121]
	v_mfma_f32_16x16x32_bf16 v[114:117], v[184:187], v[192:195], v[114:117]
	v_mfma_f32_16x16x32_bf16 v[102:105], v[176:179], v[208:211], v[102:105]
	v_mfma_f32_16x16x32_bf16 v[98:101], v[184:187], v[208:211], v[98:101]
	v_mfma_f32_16x16x32_bf16 v[86:89], v[176:179], v[216:219], v[86:89]
	v_mfma_f32_16x16x32_bf16 v[82:85], v[184:187], v[216:219], v[82:85]
	v_mfma_f32_16x16x32_bf16 v[70:73], v[176:179], v[224:227], v[70:73]
	v_mfma_f32_16x16x32_bf16 v[66:69], v[184:187], v[224:227], v[66:69]
	v_mfma_f32_16x16x32_bf16 v[118:121], v[180:183], v[204:207], v[118:121]
	v_mfma_f32_16x16x32_bf16 v[114:117], v[188:191], v[204:207], v[114:117]
	v_mfma_f32_16x16x32_bf16 v[102:105], v[180:183], v[212:215], v[102:105]
	v_mfma_f32_16x16x32_bf16 v[98:101], v[188:191], v[212:215], v[98:101]
	v_mfma_f32_16x16x32_bf16 v[86:89], v[180:183], v[220:223], v[86:89]
	v_mfma_f32_16x16x32_bf16 v[82:85], v[188:191], v[220:223], v[82:85]
	v_mfma_f32_16x16x32_bf16 v[70:73], v[180:183], v[228:231], v[70:73]
	v_mfma_f32_16x16x32_bf16 v[66:69], v[188:191], v[228:231], v[66:69]
	s_setprio 0
	s_barrier
	s_mov_b32 m0, s46
	s_add_u32 s22, s22, 0x80
	s_addc_u32 s23, s23, 0
	global_load_lds_dwordx4 v132, s[22:23]
	s_mov_b32 m0, s47
	s_add_u32 s60, s24, 0xfff00080
	s_addc_u32 s61, s25, -1
	global_load_lds_dwordx4 v136, s[22:23]
	s_mov_b32 m0, s48
	s_add_u32 s22, s22, 0x100000
	s_addc_u32 s23, s23, 0
	global_load_lds_dwordx4 v132, s[22:23]
	s_mov_b32 m0, s49
	ds_read_b128 v[192:195], v150 offset:49152
	global_load_lds_dwordx4 v136, s[22:23]
	s_mov_b32 m0, s35
	ds_read_b128 v[204:207], v150 offset:50176
	global_load_lds_dwordx4 v130, s[60:61]
	s_mov_b32 m0, s36
	ds_read_b128 v[208:211], v150 offset:51200
	global_load_lds_dwordx4 v134, s[60:61]
	ds_read_b128 v[212:215], v150 offset:52224
	ds_read_b128 v[216:219], v150 offset:53248
	ds_read_b128 v[220:223], v150 offset:54272
	ds_read_b128 v[224:227], v150 offset:55296
	ds_read_b128 v[228:231], v150 offset:56320
	s_waitcnt vmcnt(8)
	s_waitcnt lgkmcnt(0)
	s_barrier
	s_setprio 1
	s_waitcnt lgkmcnt(0)
	v_mfma_f32_16x16x32_bf16 v[62:65], v[142:145], v[192:195], v[62:65]
	v_mfma_f32_16x16x32_bf16 v[58:61], v[158:161], v[192:195], v[58:61]
	v_mfma_f32_16x16x32_bf16 v[46:49], v[142:145], v[208:211], v[46:49]
	v_mfma_f32_16x16x32_bf16 v[42:45], v[158:161], v[208:211], v[42:45]
	v_mfma_f32_16x16x32_bf16 v[30:33], v[142:145], v[216:219], v[30:33]
	v_mfma_f32_16x16x32_bf16 v[26:29], v[158:161], v[216:219], v[26:29]
	v_mfma_f32_16x16x32_bf16 v[14:17], v[142:145], v[224:227], v[14:17]
	v_mfma_f32_16x16x32_bf16 v[10:13], v[158:161], v[224:227], v[10:13]
	v_mfma_f32_16x16x32_bf16 v[62:65], v[154:157], v[204:207], v[62:65]
	v_mfma_f32_16x16x32_bf16 v[58:61], v[168:171], v[204:207], v[58:61]
	v_mfma_f32_16x16x32_bf16 v[46:49], v[154:157], v[212:215], v[46:49]
	v_mfma_f32_16x16x32_bf16 v[42:45], v[168:171], v[212:215], v[42:45]
	v_mfma_f32_16x16x32_bf16 v[30:33], v[154:157], v[220:223], v[30:33]
	v_mfma_f32_16x16x32_bf16 v[26:29], v[168:171], v[220:223], v[26:29]
	v_mfma_f32_16x16x32_bf16 v[14:17], v[154:157], v[228:231], v[14:17]
	v_mfma_f32_16x16x32_bf16 v[10:13], v[168:171], v[228:231], v[10:13]
	s_setprio 0
	s_setprio 1
	v_mfma_f32_16x16x32_bf16 v[54:57], v[176:179], v[192:195], v[54:57]
	v_mfma_f32_16x16x32_bf16 v[50:53], v[184:187], v[192:195], v[50:53]
	v_mfma_f32_16x16x32_bf16 v[38:41], v[176:179], v[208:211], v[38:41]
	v_mfma_f32_16x16x32_bf16 v[34:37], v[184:187], v[208:211], v[34:37]
	v_mfma_f32_16x16x32_bf16 v[22:25], v[176:179], v[216:219], v[22:25]
	v_mfma_f32_16x16x32_bf16 v[18:21], v[184:187], v[216:219], v[18:21]
	v_mfma_f32_16x16x32_bf16 v[6:9], v[176:179], v[224:227], v[6:9]
	v_mfma_f32_16x16x32_bf16 v[2:5], v[184:187], v[224:227], v[2:5]
	v_mfma_f32_16x16x32_bf16 v[54:57], v[180:183], v[204:207], v[54:57]
	v_mfma_f32_16x16x32_bf16 v[50:53], v[188:191], v[204:207], v[50:53]
	v_mfma_f32_16x16x32_bf16 v[38:41], v[180:183], v[212:215], v[38:41]
	v_mfma_f32_16x16x32_bf16 v[34:37], v[188:191], v[212:215], v[34:37]
	v_mfma_f32_16x16x32_bf16 v[22:25], v[180:183], v[220:223], v[22:25]
	v_mfma_f32_16x16x32_bf16 v[18:21], v[188:191], v[220:223], v[18:21]
	v_mfma_f32_16x16x32_bf16 v[6:9], v[180:183], v[228:231], v[6:9]
	v_mfma_f32_16x16x32_bf16 v[2:5], v[188:191], v[228:231], v[2:5]
	s_setprio 0
	s_barrier
	s_add_i32 s57, s57, 2
	s_add_u32 s20, s20, 0x100
	s_addc_u32 s21, s21, 0
	s_add_u32 s55, s55, 0x100
	s_addc_u32 s56, s56, 0
	s_cmp_gt_u32 s57, 61
	s_cbranch_scc0 .LBB0_2373
	s_and_b64 vcc, exec, s[16:17]
	s_cbranch_vccz .LBB0_2376
	s_barrier

.LBB0_2618:
	s_mov_b32 m0, s46
	ds_read_b128 v[142:145], v156
	global_load_lds_dwordx4 v138, s[28:29]
	s_mov_b32 m0, s47
	ds_read_b128 v[168:171], v156 offset:1024
	global_load_lds_dwordx4 v140, s[28:29]
	ds_read_b128 v[172:175], v156 offset:2048
	ds_read_b128 v[176:179], v156 offset:3072
	ds_read_b128 v[180:183], v157
	ds_read_b128 v[184:187], v157 offset:1024
	ds_read_b128 v[188:191], v157 offset:2048
	ds_read_b128 v[192:195], v157 offset:3072
	s_add_u32 s30, s28, 0xffd50080
	s_addc_u32 s31, s29, -1
	s_cmpk_eq_i32 s62, 0xa8
	s_cselect_b32 s35, s25, s31
	s_cselect_b32 s34, s24, s30
	s_cselect_b32 s31, s23, s61
	s_cselect_b32 s30, s22, s60
	ds_read_b128 v[196:199], v158
	ds_read_b128 v[200:203], v158 offset:1024
	ds_read_b128 v[204:207], v158 offset:2048
	ds_read_b128 v[208:211], v158 offset:3072
	ds_read_b128 v[212:215], v158 offset:4096
	ds_read_b128 v[216:219], v158 offset:5120
	ds_read_b128 v[220:223], v158 offset:6144
	ds_read_b128 v[224:227], v158 offset:7168
	s_waitcnt vmcnt(8)
	s_waitcnt lgkmcnt(0)
	s_barrier
	s_setprio 1
	s_waitcnt lgkmcnt(0)
	v_mfma_f32_16x16x32_bf16 v[126:129], v[142:145], v[196:199], v[126:129]
	v_mfma_f32_16x16x32_bf16 v[122:125], v[172:175], v[196:199], v[122:125]
	v_mfma_f32_16x16x32_bf16 v[110:113], v[142:145], v[204:207], v[110:113]
	v_mfma_f32_16x16x32_bf16 v[106:109], v[172:175], v[204:207], v[106:109]
	v_mfma_f32_16x16x32_bf16 v[94:97], v[142:145], v[212:215], v[94:97]
	v_mfma_f32_16x16x32_bf16 v[90:93], v[172:175], v[212:215], v[90:93]
	v_mfma_f32_16x16x32_bf16 v[78:81], v[142:145], v[220:223], v[78:81]
	v_mfma_f32_16x16x32_bf16 v[74:77], v[172:175], v[220:223], v[74:77]
	v_mfma_f32_16x16x32_bf16 v[126:129], v[168:171], v[200:203], v[126:129]
	v_mfma_f32_16x16x32_bf16 v[122:125], v[176:179], v[200:203], v[122:125]
	v_mfma_f32_16x16x32_bf16 v[110:113], v[168:171], v[208:211], v[110:113]
	v_mfma_f32_16x16x32_bf16 v[106:109], v[176:179], v[208:211], v[106:109]
	v_mfma_f32_16x16x32_bf16 v[94:97], v[168:171], v[216:219], v[94:97]
	v_mfma_f32_16x16x32_bf16 v[90:93], v[176:179], v[216:219], v[90:93]
	v_mfma_f32_16x16x32_bf16 v[78:81], v[168:171], v[224:227], v[78:81]
	v_mfma_f32_16x16x32_bf16 v[74:77], v[176:179], v[224:227], v[74:77]
	s_setprio 0
	s_setprio 1
	v_mfma_f32_16x16x32_bf16 v[118:121], v[180:183], v[196:199], v[118:121]
	v_mfma_f32_16x16x32_bf16 v[114:117], v[188:191], v[196:199], v[114:117]
	v_mfma_f32_16x16x32_bf16 v[102:105], v[180:183], v[204:207], v[102:105]
	v_mfma_f32_16x16x32_bf16 v[98:101], v[188:191], v[204:207], v[98:101]
	v_mfma_f32_16x16x32_bf16 v[86:89], v[180:183], v[212:215], v[86:89]
	v_mfma_f32_16x16x32_bf16 v[82:85], v[188:191], v[212:215], v[82:85]
	v_mfma_f32_16x16x32_bf16 v[70:73], v[180:183], v[220:223], v[70:73]
	v_mfma_f32_16x16x32_bf16 v[66:69], v[188:191], v[220:223], v[66:69]
	v_mfma_f32_16x16x32_bf16 v[118:121], v[184:187], v[200:203], v[118:121]
	v_mfma_f32_16x16x32_bf16 v[114:117], v[192:195], v[200:203], v[114:117]
	v_mfma_f32_16x16x32_bf16 v[102:105], v[184:187], v[208:211], v[102:105]
	v_mfma_f32_16x16x32_bf16 v[98:101], v[192:195], v[208:211], v[98:101]
	v_mfma_f32_16x16x32_bf16 v[86:89], v[184:187], v[216:219], v[86:89]
	v_mfma_f32_16x16x32_bf16 v[82:85], v[192:195], v[216:219], v[82:85]
	v_mfma_f32_16x16x32_bf16 v[70:73], v[184:187], v[224:227], v[70:73]
	v_mfma_f32_16x16x32_bf16 v[66:69], v[192:195], v[224:227], v[66:69]
	s_setprio 0
	s_barrier
	s_mov_b32 m0, s48
	s_add_u32 s64, s30, 0x2b0000
	global_load_lds_dwordx4 v132, s[30:31]
	s_mov_b32 m0, s49
	s_addc_u32 s65, s31, 0
	global_load_lds_dwordx4 v136, s[30:31]
	s_mov_b32 m0, s50
	ds_read_b128 v[196:199], v158 offset:16384
	global_load_lds_dwordx4 v132, s[64:65]
	s_mov_b32 m0, s51
	ds_read_b128 v[200:203], v158 offset:17408
	global_load_lds_dwordx4 v136, s[64:65]
	s_mov_b32 m0, s39
	ds_read_b128 v[204:207], v158 offset:18432
	global_load_lds_dwordx4 v130, s[34:35]
	s_mov_b32 m0, s40
	ds_read_b128 v[208:211], v158 offset:19456
	global_load_lds_dwordx4 v134, s[34:35]
	ds_read_b128 v[212:215], v158 offset:20480
	ds_read_b128 v[216:219], v158 offset:21504
	ds_read_b128 v[220:223], v158 offset:22528
	ds_read_b128 v[224:227], v158 offset:23552
	s_waitcnt vmcnt(8)
	s_waitcnt lgkmcnt(0)
	s_barrier
	s_setprio 1
	s_waitcnt lgkmcnt(0)
	v_mfma_f32_16x16x32_bf16 v[62:65], v[142:145], v[196:199], v[62:65]
	v_mfma_f32_16x16x32_bf16 v[58:61], v[172:175], v[196:199], v[58:61]
	v_mfma_f32_16x16x32_bf16 v[46:49], v[142:145], v[204:207], v[46:49]
	v_mfma_f32_16x16x32_bf16 v[42:45], v[172:175], v[204:207], v[42:45]
	v_mfma_f32_16x16x32_bf16 v[30:33], v[142:145], v[212:215], v[30:33]
	v_mfma_f32_16x16x32_bf16 v[26:29], v[172:175], v[212:215], v[26:29]
	v_mfma_f32_16x16x32_bf16 v[14:17], v[142:145], v[220:223], v[14:17]
	v_mfma_f32_16x16x32_bf16 v[10:13], v[172:175], v[220:223], v[10:13]
	v_mfma_f32_16x16x32_bf16 v[62:65], v[168:171], v[200:203], v[62:65]
	v_mfma_f32_16x16x32_bf16 v[58:61], v[176:179], v[200:203], v[58:61]
	v_mfma_f32_16x16x32_bf16 v[46:49], v[168:171], v[208:211], v[46:49]
	v_mfma_f32_16x16x32_bf16 v[42:45], v[176:179], v[208:211], v[42:45]
	v_mfma_f32_16x16x32_bf16 v[30:33], v[168:171], v[216:219], v[30:33]
	v_mfma_f32_16x16x32_bf16 v[26:29], v[176:179], v[216:219], v[26:29]
	v_mfma_f32_16x16x32_bf16 v[14:17], v[168:171], v[224:227], v[14:17]
	v_mfma_f32_16x16x32_bf16 v[10:13], v[176:179], v[224:227], v[10:13]
	s_setprio 0
	s_setprio 1
	v_mfma_f32_16x16x32_bf16 v[54:57], v[180:183], v[196:199], v[54:57]
	v_mfma_f32_16x16x32_bf16 v[50:53], v[188:191], v[196:199], v[50:53]
	v_mfma_f32_16x16x32_bf16 v[38:41], v[180:183], v[204:207], v[38:41]
	v_mfma_f32_16x16x32_bf16 v[34:37], v[188:191], v[204:207], v[34:37]
	v_mfma_f32_16x16x32_bf16 v[22:25], v[180:183], v[212:215], v[22:25]
	v_mfma_f32_16x16x32_bf16 v[18:21], v[188:191], v[212:215], v[18:21]
	v_mfma_f32_16x16x32_bf16 v[6:9], v[180:183], v[220:223], v[6:9]
	v_mfma_f32_16x16x32_bf16 v[2:5], v[188:191], v[220:223], v[2:5]
	v_mfma_f32_16x16x32_bf16 v[54:57], v[184:187], v[200:203], v[54:57]
	v_mfma_f32_16x16x32_bf16 v[50:53], v[192:195], v[200:203], v[50:53]
	v_mfma_f32_16x16x32_bf16 v[38:41], v[184:187], v[208:211], v[38:41]
	v_mfma_f32_16x16x32_bf16 v[34:37], v[192:195], v[208:211], v[34:37]
	v_mfma_f32_16x16x32_bf16 v[22:25], v[184:187], v[216:219], v[22:25]
	v_mfma_f32_16x16x32_bf16 v[18:21], v[192:195], v[216:219], v[18:21]
	v_mfma_f32_16x16x32_bf16 v[6:9], v[184:187], v[224:227], v[6:9]
	v_mfma_f32_16x16x32_bf16 v[2:5], v[192:195], v[224:227], v[2:5]
	s_setprio 0
	s_barrier
	s_add_u32 s34, s34, 0x2b0000
	s_addc_u32 s35, s35, 0
	s_mov_b32 m0, s41
	ds_read_b128 v[142:145], v159
	global_load_lds_dwordx4 v130, s[34:35]
	s_mov_b32 m0, s42
	ds_read_b128 v[168:171], v159 offset:1024
	global_load_lds_dwordx4 v134, s[34:35]
	ds_read_b128 v[172:175], v159 offset:2048
	ds_read_b128 v[176:179], v159 offset:3072
	ds_read_b128 v[180:183], v160
	ds_read_b128 v[184:187], v160 offset:1024
	ds_read_b128 v[188:191], v160 offset:2048
	ds_read_b128 v[192:195], v160 offset:3072
	ds_read_b128 v[196:199], v158 offset:32768
	ds_read_b128 v[200:203], v158 offset:33792
	ds_read_b128 v[204:207], v158 offset:34816
	ds_read_b128 v[208:211], v158 offset:35840
	ds_read_b128 v[212:215], v158 offset:36864
	ds_read_b128 v[216:219], v158 offset:37888
	ds_read_b128 v[220:223], v158 offset:38912
	ds_read_b128 v[224:227], v158 offset:39936
	s_waitcnt vmcnt(8)
	s_waitcnt lgkmcnt(0)
	s_barrier
	s_setprio 1
	s_waitcnt lgkmcnt(0)
	v_mfma_f32_16x16x32_bf16 v[126:129], v[142:145], v[196:199], v[126:129]
	v_mfma_f32_16x16x32_bf16 v[122:125], v[172:175], v[196:199], v[122:125]
	v_mfma_f32_16x16x32_bf16 v[110:113], v[142:145], v[204:207], v[110:113]
	v_mfma_f32_16x16x32_bf16 v[106:109], v[172:175], v[204:207], v[106:109]
	v_mfma_f32_16x16x32_bf16 v[94:97], v[142:145], v[212:215], v[94:97]
	v_mfma_f32_16x16x32_bf16 v[90:93], v[172:175], v[212:215], v[90:93]
	v_mfma_f32_16x16x32_bf16 v[78:81], v[142:145], v[220:223], v[78:81]
	v_mfma_f32_16x16x32_bf16 v[74:77], v[172:175], v[220:223], v[74:77]
	v_mfma_f32_16x16x32_bf16 v[126:129], v[168:171], v[200:203], v[126:129]
	v_mfma_f32_16x16x32_bf16 v[122:125], v[176:179], v[200:203], v[122:125]
	v_mfma_f32_16x16x32_bf16 v[110:113], v[168:171], v[208:211], v[110:113]
	v_mfma_f32_16x16x32_bf16 v[106:109], v[176:179], v[208:211], v[106:109]
	v_mfma_f32_16x16x32_bf16 v[94:97], v[168:171], v[216:219], v[94:97]
	v_mfma_f32_16x16x32_bf16 v[90:93], v[176:179], v[216:219], v[90:93]
	v_mfma_f32_16x16x32_bf16 v[78:81], v[168:171], v[224:227], v[78:81]
	v_mfma_f32_16x16x32_bf16 v[74:77], v[176:179], v[224:227], v[74:77]
	s_setprio 0
	s_setprio 1
	v_mfma_f32_16x16x32_bf16 v[118:121], v[180:183], v[196:199], v[118:121]
	v_mfma_f32_16x16x32_bf16 v[114:117], v[188:191], v[196:199], v[114:117]
	v_mfma_f32_16x16x32_bf16 v[102:105], v[180:183], v[204:207], v[102:105]
	v_mfma_f32_16x16x32_bf16 v[98:101], v[188:191], v[204:207], v[98:101]
	v_mfma_f32_16x16x32_bf16 v[86:89], v[180:183], v[212:215], v[86:89]
	v_mfma_f32_16x16x32_bf16 v[82:85], v[188:191], v[212:215], v[82:85]
	v_mfma_f32_16x16x32_bf16 v[70:73], v[180:183], v[220:223], v[70:73]
	v_mfma_f32_16x16x32_bf16 v[66:69], v[188:191], v[220:223], v[66:69]
	v_mfma_f32_16x16x32_bf16 v[118:121], v[184:187], v[200:203], v[118:121]
	v_mfma_f32_16x16x32_bf16 v[114:117], v[192:195], v[200:203], v[114:117]
	v_mfma_f32_16x16x32_bf16 v[102:105], v[184:187], v[208:211], v[102:105]
	v_mfma_f32_16x16x32_bf16 v[98:101], v[192:195], v[208:211], v[98:101]
	v_mfma_f32_16x16x32_bf16 v[86:89], v[184:187], v[216:219], v[86:89]
	v_mfma_f32_16x16x32_bf16 v[82:85], v[192:195], v[216:219], v[82:85]
	v_mfma_f32_16x16x32_bf16 v[70:73], v[184:187], v[224:227], v[70:73]
	v_mfma_f32_16x16x32_bf16 v[66:69], v[192:195], v[224:227], v[66:69]
	s_setprio 0
	s_barrier
	s_mov_b32 m0, s52
	s_add_u32 s30, s30, 0x80
	s_addc_u32 s31, s31, 0
	global_load_lds_dwordx4 v132, s[30:31]
	s_mov_b32 m0, s53
	s_add_u32 s64, s34, 0xffd50080
	s_addc_u32 s65, s35, -1
	global_load_lds_dwordx4 v136, s[30:31]
	s_mov_b32 m0, s54
	s_add_u32 s30, s30, 0x2b0000
	s_addc_u32 s31, s31, 0
	global_load_lds_dwordx4 v132, s[30:31]
	s_mov_b32 m0, s55
	ds_read_b128 v[196:199], v158 offset:49152
	global_load_lds_dwordx4 v136, s[30:31]
	s_mov_b32 m0, s44
	ds_read_b128 v[200:203], v158 offset:50176
	global_load_lds_dwordx4 v130, s[64:65]
	s_mov_b32 m0, s45
	ds_read_b128 v[204:207], v158 offset:51200
	global_load_lds_dwordx4 v134, s[64:65]
	ds_read_b128 v[208:211], v158 offset:52224
	ds_read_b128 v[212:215], v158 offset:53248
	ds_read_b128 v[216:219], v158 offset:54272
	ds_read_b128 v[220:223], v158 offset:55296
	ds_read_b128 v[224:227], v158 offset:56320
	s_waitcnt vmcnt(8)
	s_waitcnt lgkmcnt(0)
	s_barrier
	s_setprio 1
	s_waitcnt lgkmcnt(0)
	v_mfma_f32_16x16x32_bf16 v[62:65], v[142:145], v[196:199], v[62:65]
	v_mfma_f32_16x16x32_bf16 v[58:61], v[172:175], v[196:199], v[58:61]
	v_mfma_f32_16x16x32_bf16 v[46:49], v[142:145], v[204:207], v[46:49]
	v_mfma_f32_16x16x32_bf16 v[42:45], v[172:175], v[204:207], v[42:45]
	v_mfma_f32_16x16x32_bf16 v[30:33], v[142:145], v[212:215], v[30:33]
	v_mfma_f32_16x16x32_bf16 v[26:29], v[172:175], v[212:215], v[26:29]
	v_mfma_f32_16x16x32_bf16 v[14:17], v[142:145], v[220:223], v[14:17]
	v_mfma_f32_16x16x32_bf16 v[10:13], v[172:175], v[220:223], v[10:13]
	v_mfma_f32_16x16x32_bf16 v[62:65], v[168:171], v[200:203], v[62:65]
	v_mfma_f32_16x16x32_bf16 v[58:61], v[176:179], v[200:203], v[58:61]
	v_mfma_f32_16x16x32_bf16 v[46:49], v[168:171], v[208:211], v[46:49]
	v_mfma_f32_16x16x32_bf16 v[42:45], v[176:179], v[208:211], v[42:45]
	v_mfma_f32_16x16x32_bf16 v[30:33], v[168:171], v[216:219], v[30:33]
	v_mfma_f32_16x16x32_bf16 v[26:29], v[176:179], v[216:219], v[26:29]
	v_mfma_f32_16x16x32_bf16 v[14:17], v[168:171], v[224:227], v[14:17]
	v_mfma_f32_16x16x32_bf16 v[10:13], v[176:179], v[224:227], v[10:13]
	s_setprio 0
	s_setprio 1
	v_mfma_f32_16x16x32_bf16 v[54:57], v[180:183], v[196:199], v[54:57]
	v_mfma_f32_16x16x32_bf16 v[50:53], v[188:191], v[196:199], v[50:53]
	v_mfma_f32_16x16x32_bf16 v[38:41], v[180:183], v[204:207], v[38:41]
	v_mfma_f32_16x16x32_bf16 v[34:37], v[188:191], v[204:207], v[34:37]
	v_mfma_f32_16x16x32_bf16 v[22:25], v[180:183], v[212:215], v[22:25]
	v_mfma_f32_16x16x32_bf16 v[18:21], v[188:191], v[212:215], v[18:21]
	v_mfma_f32_16x16x32_bf16 v[6:9], v[180:183], v[220:223], v[6:9]
	v_mfma_f32_16x16x32_bf16 v[2:5], v[188:191], v[220:223], v[2:5]
	v_mfma_f32_16x16x32_bf16 v[54:57], v[184:187], v[200:203], v[54:57]
	v_mfma_f32_16x16x32_bf16 v[50:53], v[192:195], v[200:203], v[50:53]
	v_mfma_f32_16x16x32_bf16 v[38:41], v[184:187], v[208:211], v[38:41]
	v_mfma_f32_16x16x32_bf16 v[34:37], v[192:195], v[208:211], v[34:37]
	v_mfma_f32_16x16x32_bf16 v[22:25], v[184:187], v[216:219], v[22:25]
	v_mfma_f32_16x16x32_bf16 v[18:21], v[192:195], v[216:219], v[18:21]
	v_mfma_f32_16x16x32_bf16 v[6:9], v[184:187], v[224:227], v[6:9]
	v_mfma_f32_16x16x32_bf16 v[2:5], v[192:195], v[224:227], v[2:5]
	s_setprio 0
	s_barrier
	s_add_i32 s62, s62, 2
	s_add_u32 s28, s28, 0x100
	s_addc_u32 s29, s29, 0
	s_add_u32 s60, s60, 0x100
	s_addc_u32 s61, s61, 0
	s_cmpk_gt_u32 s62, 0xa9
	s_cbranch_scc0 .LBB0_2618
	s_and_b64 vcc, exec, s[12:13]
	s_cbranch_vccz .LBB0_2621
	s_barrier
